# PEER gather passes: next 8-row group requested while current group converts (software prefetch one group ahead), pass B converts per row pair; attention LDS-DMA v2
# speedup vs baseline: 1.0445x; 1.0041x over previous
.Lau_entry:
	v_and_b32_e32 v3, 63, v0
	v_lshrrev_b32_e32 v4, 6, v0
	v_readfirstlane_b32 s75, v138
	v_and_b32_e32 v1, 15, v3
	v_readfirstlane_b32 s76, v4
	v_lshrrev_b32_e32 v2, 4, v3
	s_lshl_b32 s76, s76, 11
	s_add_i32 s76, s76, 0x24000
	v_lshl_add_u32 v4, v2, 2, v138
	ds_read2_b32 v[10:11], v4 offset0:0 offset1:4
	ds_read2_b32 v[12:13], v4 offset0:8 offset1:12
	ds_read2_b32 v[14:15], v4 offset0:16 offset1:20
	ds_read2_b32 v[16:17], v4 offset0:24 offset1:28
	ds_read2_b32 v[18:19], v4 offset0:32 offset1:36
	ds_read2_b32 v[20:21], v4 offset0:40 offset1:44
	ds_read2_b32 v[22:23], v4 offset0:48 offset1:52
	ds_read2_b32 v[24:25], v4 offset0:56 offset1:60
	ds_read2_b32 v[26:27], v4 offset0:64 offset1:68
	ds_read2_b32 v[28:29], v4 offset0:72 offset1:76
	ds_read2_b32 v[30:31], v4 offset0:80 offset1:84
	ds_read2_b32 v[32:33], v4 offset0:88 offset1:92
	ds_read2_b32 v[34:35], v4 offset0:96 offset1:100
	ds_read2_b32 v[36:37], v4 offset0:104 offset1:108
	ds_read2_b32 v[38:39], v4 offset0:112 offset1:116
	ds_read2_b32 v[40:41], v4 offset0:120 offset1:124
	ds_read2_b32 v[42:43], v4 offset0:128 offset1:132
	ds_read2_b32 v[44:45], v4 offset0:136 offset1:140
	ds_read2_b32 v[46:47], v4 offset0:144 offset1:148
	ds_read2_b32 v[48:49], v4 offset0:152 offset1:156
	ds_read2_b32 v[50:51], v4 offset0:160 offset1:164
	ds_read2_b32 v[52:53], v4 offset0:168 offset1:172
	ds_read2_b32 v[54:55], v4 offset0:176 offset1:180
	ds_read2_b32 v[56:57], v4 offset0:184 offset1:188
	ds_read2_b32 v[58:59], v4 offset0:192 offset1:196
	ds_read2_b32 v[60:61], v4 offset0:200 offset1:204
	ds_read2_b32 v[62:63], v4 offset0:208 offset1:212
	ds_read2_b32 v[64:65], v4 offset0:216 offset1:220
	ds_read2_b32 v[66:67], v4 offset0:224 offset1:228
	ds_read2_b32 v[68:69], v4 offset0:232 offset1:236
	ds_read2_b32 v[70:71], v4 offset0:240 offset1:244
	ds_read2_b32 v[72:73], v4 offset0:248 offset1:252
	v_readlane_b32 s40, v251, 27
	v_readlane_b32 s41, v251, 28
	v_readlane_b32 s42, v251, 29
	v_readlane_b32 s43, v251, 30
	v_readlane_b32 s44, v251, 31
	v_readlane_b32 s45, v251, 32
	v_readlane_b32 s46, v251, 49
	v_readlane_b32 s47, v251, 50
	s_lshl_b32 s8, s70, 11
	s_lshl_b32 s9, s72, 9
	s_add_u32 s56, s40, s8
	s_addc_u32 s57, s41, 0
	s_add_u32 s50, s42, s9
	s_addc_u32 s51, s43, 0
	s_add_u32 s52, s44, s9
	s_addc_u32 s53, s45, 0
	s_add_u32 s58, s46, s8
	s_addc_u32 s59, s47, 0
	v_lshlrev_b32_e32 v5, 1, v2
	v_xor_b32_e32 v5, v1, v5
	v_lshlrev_b32_e32 v5, 4, v5
	v_xor_b32_e32 v6, 0x80, v5
	v_and_b32_e32 v7, 3, v1
	v_and_b32_e32 v8, 8, v1
	v_lshl_or_b32 v8, v7, 1, v8
	v_or_b32_e32 v9, 0, v2
	v_xor_b32_e32 v9, v9, v8
	v_lshlrev_b32_e32 v9, 4, v9
	v_lshl_add_u32 v9, v1, 8, v9
	v_add_u32_e32 v74, s75, v9
	v_or_b32_e32 v9, 4, v2
	v_xor_b32_e32 v9, v9, v8
	v_lshlrev_b32_e32 v9, 4, v9
	v_lshl_add_u32 v9, v1, 8, v9
	v_add_u32_e32 v75, s75, v9
	v_or_b32_e32 v9, 8, v2
	v_xor_b32_e32 v9, v9, v8
	v_lshlrev_b32_e32 v9, 4, v9
	v_lshl_add_u32 v9, v1, 8, v9
	v_add_u32_e32 v76, s75, v9
	v_or_b32_e32 v9, 12, v2
	v_xor_b32_e32 v9, v9, v8
	v_lshlrev_b32_e32 v9, 4, v9
	v_lshl_add_u32 v9, v1, 8, v9
	v_add_u32_e32 v77, s75, v9
	v_lshrrev_b32_e32 v128, 2, v1
	v_lshl_or_b32 v129, v2, 3, v128
	v_and_b32_e32 v130, 1, v2
	v_lshl_or_b32 v130, v130, 2, v128
	v_lshlrev_b32_e32 v129, 8, v129
	v_lshl_add_u32 v129, v7, 3, v129
	v_add_u32_e32 v129, s75, v129
	v_xor_b32_e32 v9, 0, v130
	v_lshl_add_u32 v78, v9, 5, v129
	v_xor_b32_e32 v9, 1, v130
	v_lshl_add_u32 v79, v9, 5, v129
	v_xor_b32_e32 v9, 2, v130
	v_lshl_add_u32 v80, v9, 5, v129
	v_xor_b32_e32 v9, 3, v130
	v_lshl_add_u32 v81, v9, 5, v129
	v_xor_b32_e32 v9, 4, v130
	v_lshl_add_u32 v82, v9, 5, v129
	v_xor_b32_e32 v9, 5, v130
	v_lshl_add_u32 v83, v9, 5, v129
	v_xor_b32_e32 v9, 6, v130
	v_lshl_add_u32 v84, v9, 5, v129
	v_xor_b32_e32 v9, 7, v130
	v_lshl_add_u32 v85, v9, 5, v129
	v_lshl_add_u32 v86, v1, 4, s75
	v_lshl_add_u32 v87, v3, 4, s75
	v_lshl_add_u32 v88, v3, 1, s76
	v_cmp_gt_u32_e64 s[20:21], 4, v1
	v_lshlrev_b32_e32 v9, 4, v2
	v_lshl_add_u32 v128, v7, 9, v9
	v_add_u32_e32 v128, s76, v128
	v_add_u32_e32 v131, 0x22000, v9
	v_cndmask_b32_e64 v89, v131, v128, s[20:21]
	v_lshrrev_b32_e32 v128, 3, v1
	v_add_u32_e32 v128, v128, v1
	v_lshl_add_u32 v132, v128, 4, s75
	v_add_u32_e32 v132, 0x400, v132
	v_and_b32_e32 v128, 3, v3
	v_lshrrev_b32_e32 v129, 2, v3
	v_mul_u32_u24_e32 v131, 0x90, v129
	v_lshl_add_u32 v131, v128, 2, v131
	v_add_u32_e32 v133, s75, v131
	v_add_u32_e32 v133, 0x400, v133
	v_lshlrev_b32_e32 v129, 4, v129
	v_lshl_add_u32 v90, v128, 8, v129
	v_lshl_add_u32 v91, v7, 8, v9
	v_mov_b32_e32 v128, 0
	v_mov_b32_e32 v129, 0
	v_lshlrev_b32_e32 v9, 3, v3
	v_add_u32_e32 v9, 0x22000, v9
	ds_write_b64 v9, v[128:129]
	v_cmp_gt_u32_e64 s[24:25], s73, v3
	v_add_u32_e32 v9, 64, v3
	v_cmp_gt_u32_e64 s[26:27], s73, v9
	v_add_u32_e32 v9, 0x80, v3
	v_cmp_gt_u32_e64 s[28:29], s73, v9
	v_add_u32_e32 v9, 0xc0, v3
	v_cmp_gt_u32_e64 s[30:31], s73, v9
	s_waitcnt lgkmcnt(0)
	v_lshl_add_u32 v10, v10, 9, v5
	v_lshl_add_u32 v11, v11, 9, v5
	v_lshl_add_u32 v12, v12, 9, v6
	v_lshl_add_u32 v13, v13, 9, v6
	v_lshl_add_u32 v14, v14, 9, v5
	v_lshl_add_u32 v15, v15, 9, v5
	v_lshl_add_u32 v16, v16, 9, v6
	v_lshl_add_u32 v17, v17, 9, v6
	v_lshl_add_u32 v18, v18, 9, v5
	v_lshl_add_u32 v19, v19, 9, v5
	v_lshl_add_u32 v20, v20, 9, v6
	v_lshl_add_u32 v21, v21, 9, v6
	v_lshl_add_u32 v22, v22, 9, v5
	v_lshl_add_u32 v23, v23, 9, v5
	v_lshl_add_u32 v24, v24, 9, v6
	v_lshl_add_u32 v25, v25, 9, v6
	v_lshl_add_u32 v26, v26, 9, v5
	v_lshl_add_u32 v27, v27, 9, v5
	v_lshl_add_u32 v28, v28, 9, v6
	v_lshl_add_u32 v29, v29, 9, v6
	v_lshl_add_u32 v30, v30, 9, v5
	v_lshl_add_u32 v31, v31, 9, v5
	v_lshl_add_u32 v32, v32, 9, v6
	v_lshl_add_u32 v33, v33, 9, v6
	v_lshl_add_u32 v34, v34, 9, v5
	v_lshl_add_u32 v35, v35, 9, v5
	v_lshl_add_u32 v36, v36, 9, v6
	v_lshl_add_u32 v37, v37, 9, v6
	v_lshl_add_u32 v38, v38, 9, v5
	v_lshl_add_u32 v39, v39, 9, v5
	v_lshl_add_u32 v40, v40, 9, v6
	v_lshl_add_u32 v41, v41, 9, v6
	v_lshl_add_u32 v42, v42, 9, v5
	v_lshl_add_u32 v43, v43, 9, v5
	v_lshl_add_u32 v44, v44, 9, v6
	v_lshl_add_u32 v45, v45, 9, v6
	v_lshl_add_u32 v46, v46, 9, v5
	v_lshl_add_u32 v47, v47, 9, v5
	v_lshl_add_u32 v48, v48, 9, v6
	v_lshl_add_u32 v49, v49, 9, v6
	v_lshl_add_u32 v50, v50, 9, v5
	v_lshl_add_u32 v51, v51, 9, v5
	v_lshl_add_u32 v52, v52, 9, v6
	v_lshl_add_u32 v53, v53, 9, v6
	v_lshl_add_u32 v54, v54, 9, v5
	v_lshl_add_u32 v55, v55, 9, v5
	v_lshl_add_u32 v56, v56, 9, v6
	v_lshl_add_u32 v57, v57, 9, v6
	v_lshl_add_u32 v58, v58, 9, v5
	v_lshl_add_u32 v59, v59, 9, v5
	v_lshl_add_u32 v60, v60, 9, v6
	v_lshl_add_u32 v61, v61, 9, v6
	v_lshl_add_u32 v62, v62, 9, v5
	v_lshl_add_u32 v63, v63, 9, v5
	v_lshl_add_u32 v64, v64, 9, v6
	v_lshl_add_u32 v65, v65, 9, v6
	v_lshl_add_u32 v66, v66, 9, v5
	v_lshl_add_u32 v67, v67, 9, v5
	v_lshl_add_u32 v68, v68, 9, v6
	v_lshl_add_u32 v69, v69, 9, v6
	v_lshl_add_u32 v70, v70, 9, v5
	v_lshl_add_u32 v71, v71, 9, v5
	v_lshl_add_u32 v72, v72, 9, v6
	v_lshl_add_u32 v73, v73, 9, v6
	s_mov_b32 s71, 0
.Lau_g:
	s_lshl_b32 s8, s71, 8
	s_lshl_b32 s9, s71, 10
	s_add_u32 s0, s50, s8
	s_addc_u32 s1, s51, 0
	s_add_u32 s2, s52, s8
	s_addc_u32 s3, s53, 0
	s_add_u32 s4, s56, s9
	s_addc_u32 s5, s57, 0
	s_add_u32 s6, s58, s9
	s_addc_u32 s7, s59, 0
	global_load_dwordx4 v[92:95], v91, s[4:5] offset:0
	global_load_dwordx4 v[96:99], v91, s[4:5] offset:64
	global_load_dwordx4 v[100:103], v91, s[4:5] offset:128
	global_load_dwordx4 v[104:107], v91, s[4:5] offset:192
	s_add_i32 m0, s75, 0x1400
	s_nop 0
	global_load_lds_dwordx4 v10, s[0:1]
	s_add_i32 m0, s75, 0x1800
	s_nop 0
	global_load_lds_dwordx4 v11, s[0:1]
	s_add_i32 m0, s75, 0x1c00
	s_nop 0
	global_load_lds_dwordx4 v12, s[0:1]
	s_add_i32 m0, s75, 0x2000
	s_nop 0
	global_load_lds_dwordx4 v13, s[0:1]
	s_add_i32 m0, s75, 0x2400
	s_nop 0
	global_load_lds_dwordx4 v14, s[0:1]
	s_add_i32 m0, s75, 0x2800
	s_nop 0
	global_load_lds_dwordx4 v15, s[0:1]
	s_add_i32 m0, s75, 0x2c00
	s_nop 0
	global_load_lds_dwordx4 v16, s[0:1]
	s_add_i32 m0, s75, 0x3000
	s_nop 0
	global_load_lds_dwordx4 v17, s[0:1]
	s_add_i32 m0, s75, 0x3400
	s_nop 0
	global_load_lds_dwordx4 v18, s[0:1]
	s_add_i32 m0, s75, 0x3800
	s_nop 0
	global_load_lds_dwordx4 v19, s[0:1]
	s_add_i32 m0, s75, 0x3c00
	s_nop 0
	global_load_lds_dwordx4 v20, s[0:1]
	s_add_i32 m0, s75, 0x4000
	s_nop 0
	global_load_lds_dwordx4 v21, s[0:1]
	s_waitcnt vmcnt(8)
	ds_read_b128 v[108:111], v74 offset:5120
	ds_read_b128 v[112:115], v75 offset:5120
	ds_read_b128 v[116:119], v76 offset:5120
	ds_read_b128 v[120:123], v77 offset:5120
	v_cndmask_b32_e64 v92, 0, v92, s[20:21]
	v_cndmask_b32_e64 v93, 0, v93, s[20:21]
	v_cndmask_b32_e64 v94, 0, v94, s[20:21]
	v_cndmask_b32_e64 v95, 0, v95, s[20:21]
	v_cndmask_b32_e64 v96, 0, v96, s[20:21]
	v_cndmask_b32_e64 v97, 0, v97, s[20:21]
	v_cndmask_b32_e64 v98, 0, v98, s[20:21]
	v_cndmask_b32_e64 v99, 0, v99, s[20:21]
	v_cndmask_b32_e64 v100, 0, v100, s[20:21]
	v_cndmask_b32_e64 v101, 0, v101, s[20:21]
	v_cndmask_b32_e64 v102, 0, v102, s[20:21]
	v_cndmask_b32_e64 v103, 0, v103, s[20:21]
	v_cndmask_b32_e64 v104, 0, v104, s[20:21]
	v_cndmask_b32_e64 v105, 0, v105, s[20:21]
	v_cndmask_b32_e64 v106, 0, v106, s[20:21]
	v_cndmask_b32_e64 v107, 0, v107, s[20:21]
	s_waitcnt lgkmcnt(0)
	v_mfma_f32_16x16x32_bf16 v[124:127], v[92:95], v[108:111], 0
	s_add_i32 m0, s75, 0x1400
	v_mfma_f32_16x16x32_bf16 v[124:127], v[96:99], v[112:115], v[124:127]
	global_load_lds_dwordx4 v22, s[0:1]
	s_add_i32 m0, s75, 0x1800
	v_mfma_f32_16x16x32_bf16 v[124:127], v[100:103], v[116:119], v[124:127]
	global_load_lds_dwordx4 v23, s[0:1]
	s_add_i32 m0, s75, 0x1c00
	v_mfma_f32_16x16x32_bf16 v[124:127], v[104:107], v[120:123], v[124:127]
	global_load_lds_dwordx4 v24, s[0:1]
	s_add_i32 m0, s75, 0x2000
	s_nop 0
	global_load_lds_dwordx4 v25, s[0:1]
	s_nop 5
	s_mov_b64 exec, 0xffff
	ds_write_b128 v86, v[124:127] offset:1024
	s_mov_b64 exec, -1
	s_waitcnt vmcnt(8)
	ds_read_b128 v[108:111], v74 offset:9216
	ds_read_b128 v[112:115], v75 offset:9216
	ds_read_b128 v[116:119], v76 offset:9216
	ds_read_b128 v[120:123], v77 offset:9216
	s_waitcnt lgkmcnt(0)
	v_mfma_f32_16x16x32_bf16 v[124:127], v[92:95], v[108:111], 0
	s_add_i32 m0, s75, 0x2400
	v_mfma_f32_16x16x32_bf16 v[124:127], v[96:99], v[112:115], v[124:127]
	global_load_lds_dwordx4 v26, s[0:1]
	s_add_i32 m0, s75, 0x2800
	v_mfma_f32_16x16x32_bf16 v[124:127], v[100:103], v[116:119], v[124:127]
	global_load_lds_dwordx4 v27, s[0:1]
	s_add_i32 m0, s75, 0x2c00
	v_mfma_f32_16x16x32_bf16 v[124:127], v[104:107], v[120:123], v[124:127]
	global_load_lds_dwordx4 v28, s[0:1]
	s_add_i32 m0, s75, 0x3000
	s_nop 0
	global_load_lds_dwordx4 v29, s[0:1]
	s_nop 5
	s_mov_b64 exec, 0xffff
	ds_write_b128 v86, v[124:127] offset:1280
	s_mov_b64 exec, -1
	s_waitcnt vmcnt(8)
	ds_read_b128 v[108:111], v74 offset:13312
	ds_read_b128 v[112:115], v75 offset:13312
	ds_read_b128 v[116:119], v76 offset:13312
	ds_read_b128 v[120:123], v77 offset:13312
	s_waitcnt lgkmcnt(0)
	v_mfma_f32_16x16x32_bf16 v[124:127], v[92:95], v[108:111], 0
	s_add_i32 m0, s75, 0x3400
	v_mfma_f32_16x16x32_bf16 v[124:127], v[96:99], v[112:115], v[124:127]
	global_load_lds_dwordx4 v30, s[0:1]
	s_add_i32 m0, s75, 0x3800
	v_mfma_f32_16x16x32_bf16 v[124:127], v[100:103], v[116:119], v[124:127]
	global_load_lds_dwordx4 v31, s[0:1]
	s_add_i32 m0, s75, 0x3c00
	v_mfma_f32_16x16x32_bf16 v[124:127], v[104:107], v[120:123], v[124:127]
	global_load_lds_dwordx4 v32, s[0:1]
	s_add_i32 m0, s75, 0x4000
	s_nop 0
	global_load_lds_dwordx4 v33, s[0:1]
	s_nop 5
	s_mov_b64 exec, 0xffff
	ds_write_b128 v86, v[124:127] offset:1536
	s_mov_b64 exec, -1
	s_waitcnt vmcnt(8)
	ds_read_b128 v[108:111], v74 offset:5120
	ds_read_b128 v[112:115], v75 offset:5120
	ds_read_b128 v[116:119], v76 offset:5120
	ds_read_b128 v[120:123], v77 offset:5120
	s_waitcnt lgkmcnt(0)
	v_mfma_f32_16x16x32_bf16 v[124:127], v[92:95], v[108:111], 0
	s_add_i32 m0, s75, 0x1400
	v_mfma_f32_16x16x32_bf16 v[124:127], v[96:99], v[112:115], v[124:127]
	global_load_lds_dwordx4 v34, s[0:1]
	s_add_i32 m0, s75, 0x1800
	v_mfma_f32_16x16x32_bf16 v[124:127], v[100:103], v[116:119], v[124:127]
	global_load_lds_dwordx4 v35, s[0:1]
	s_add_i32 m0, s75, 0x1c00
	v_mfma_f32_16x16x32_bf16 v[124:127], v[104:107], v[120:123], v[124:127]
	global_load_lds_dwordx4 v36, s[0:1]
	s_add_i32 m0, s75, 0x2000
	s_nop 0
	global_load_lds_dwordx4 v37, s[0:1]
	s_nop 5
	s_mov_b64 exec, 0xffff
	ds_write_b128 v86, v[124:127] offset:1792
	s_mov_b64 exec, -1
	s_waitcnt vmcnt(8)
	ds_read_b128 v[108:111], v74 offset:9216
	ds_read_b128 v[112:115], v75 offset:9216
	ds_read_b128 v[116:119], v76 offset:9216
	ds_read_b128 v[120:123], v77 offset:9216
	s_waitcnt lgkmcnt(0)
	v_mfma_f32_16x16x32_bf16 v[124:127], v[92:95], v[108:111], 0
	s_add_i32 m0, s75, 0x2400
	v_mfma_f32_16x16x32_bf16 v[124:127], v[96:99], v[112:115], v[124:127]
	global_load_lds_dwordx4 v38, s[0:1]
	s_add_i32 m0, s75, 0x2800
	v_mfma_f32_16x16x32_bf16 v[124:127], v[100:103], v[116:119], v[124:127]
	global_load_lds_dwordx4 v39, s[0:1]
	s_add_i32 m0, s75, 0x2c00
	v_mfma_f32_16x16x32_bf16 v[124:127], v[104:107], v[120:123], v[124:127]
	global_load_lds_dwordx4 v40, s[0:1]
	s_add_i32 m0, s75, 0x3000
	s_nop 0
	global_load_lds_dwordx4 v41, s[0:1]
	s_nop 5
	s_mov_b64 exec, 0xffff
	ds_write_b128 v86, v[124:127] offset:2048
	s_mov_b64 exec, -1
	s_waitcnt vmcnt(8)
	ds_read_b128 v[108:111], v74 offset:13312
	ds_read_b128 v[112:115], v75 offset:13312
	ds_read_b128 v[116:119], v76 offset:13312
	ds_read_b128 v[120:123], v77 offset:13312
	s_waitcnt lgkmcnt(0)
	v_mfma_f32_16x16x32_bf16 v[124:127], v[92:95], v[108:111], 0
	s_add_i32 m0, s75, 0x3400
	v_mfma_f32_16x16x32_bf16 v[124:127], v[96:99], v[112:115], v[124:127]
	global_load_lds_dwordx4 v42, s[0:1]
	s_add_i32 m0, s75, 0x3800
	v_mfma_f32_16x16x32_bf16 v[124:127], v[100:103], v[116:119], v[124:127]
	global_load_lds_dwordx4 v43, s[0:1]
	s_add_i32 m0, s75, 0x3c00
	v_mfma_f32_16x16x32_bf16 v[124:127], v[104:107], v[120:123], v[124:127]
	global_load_lds_dwordx4 v44, s[0:1]
	s_add_i32 m0, s75, 0x4000
	s_nop 0
	global_load_lds_dwordx4 v45, s[0:1]
	s_nop 5
	s_mov_b64 exec, 0xffff
	ds_write_b128 v86, v[124:127] offset:2304
	s_mov_b64 exec, -1
	s_waitcnt vmcnt(8)
	ds_read_b128 v[108:111], v74 offset:5120
	ds_read_b128 v[112:115], v75 offset:5120
	ds_read_b128 v[116:119], v76 offset:5120
	ds_read_b128 v[120:123], v77 offset:5120
	s_waitcnt lgkmcnt(0)
	v_mfma_f32_16x16x32_bf16 v[124:127], v[92:95], v[108:111], 0
	s_add_i32 m0, s75, 0x1400
	v_mfma_f32_16x16x32_bf16 v[124:127], v[96:99], v[112:115], v[124:127]
	global_load_lds_dwordx4 v46, s[0:1]
	s_add_i32 m0, s75, 0x1800
	v_mfma_f32_16x16x32_bf16 v[124:127], v[100:103], v[116:119], v[124:127]
	global_load_lds_dwordx4 v47, s[0:1]
	s_add_i32 m0, s75, 0x1c00
	v_mfma_f32_16x16x32_bf16 v[124:127], v[104:107], v[120:123], v[124:127]
	global_load_lds_dwordx4 v48, s[0:1]
	s_add_i32 m0, s75, 0x2000
	s_nop 0
	global_load_lds_dwordx4 v49, s[0:1]
	s_nop 5
	s_mov_b64 exec, 0xffff
	ds_write_b128 v86, v[124:127] offset:2560
	s_mov_b64 exec, -1
	s_waitcnt vmcnt(8)
	ds_read_b128 v[108:111], v74 offset:9216
	ds_read_b128 v[112:115], v75 offset:9216
	ds_read_b128 v[116:119], v76 offset:9216
	ds_read_b128 v[120:123], v77 offset:9216
	s_waitcnt lgkmcnt(0)
	v_mfma_f32_16x16x32_bf16 v[124:127], v[92:95], v[108:111], 0
	s_add_i32 m0, s75, 0x2400
	v_mfma_f32_16x16x32_bf16 v[124:127], v[96:99], v[112:115], v[124:127]
	global_load_lds_dwordx4 v50, s[0:1]
	s_add_i32 m0, s75, 0x2800
	v_mfma_f32_16x16x32_bf16 v[124:127], v[100:103], v[116:119], v[124:127]
	global_load_lds_dwordx4 v51, s[0:1]
	s_add_i32 m0, s75, 0x2c00
	v_mfma_f32_16x16x32_bf16 v[124:127], v[104:107], v[120:123], v[124:127]
	global_load_lds_dwordx4 v52, s[0:1]
	s_add_i32 m0, s75, 0x3000
	s_nop 0
	global_load_lds_dwordx4 v53, s[0:1]
	s_nop 5
	s_mov_b64 exec, 0xffff
	ds_write_b128 v86, v[124:127] offset:2816
	s_mov_b64 exec, -1
	s_waitcnt vmcnt(8)
	ds_read_b128 v[108:111], v74 offset:13312
	ds_read_b128 v[112:115], v75 offset:13312
	ds_read_b128 v[116:119], v76 offset:13312
	ds_read_b128 v[120:123], v77 offset:13312
	s_waitcnt lgkmcnt(0)
	v_mfma_f32_16x16x32_bf16 v[124:127], v[92:95], v[108:111], 0
	s_add_i32 m0, s75, 0x3400
	v_mfma_f32_16x16x32_bf16 v[124:127], v[96:99], v[112:115], v[124:127]
	global_load_lds_dwordx4 v54, s[0:1]
	s_add_i32 m0, s75, 0x3800
	v_mfma_f32_16x16x32_bf16 v[124:127], v[100:103], v[116:119], v[124:127]
	global_load_lds_dwordx4 v55, s[0:1]
	s_add_i32 m0, s75, 0x3c00
	v_mfma_f32_16x16x32_bf16 v[124:127], v[104:107], v[120:123], v[124:127]
	global_load_lds_dwordx4 v56, s[0:1]
	s_add_i32 m0, s75, 0x4000
	s_nop 0
	global_load_lds_dwordx4 v57, s[0:1]
	s_nop 5
	s_mov_b64 exec, 0xffff
	ds_write_b128 v86, v[124:127] offset:3072
	s_mov_b64 exec, -1
	s_waitcnt vmcnt(8)
	ds_read_b128 v[108:111], v74 offset:5120
	ds_read_b128 v[112:115], v75 offset:5120
	ds_read_b128 v[116:119], v76 offset:5120
	ds_read_b128 v[120:123], v77 offset:5120
	s_waitcnt lgkmcnt(0)
	v_mfma_f32_16x16x32_bf16 v[124:127], v[92:95], v[108:111], 0
	s_add_i32 m0, s75, 0x1400
	v_mfma_f32_16x16x32_bf16 v[124:127], v[96:99], v[112:115], v[124:127]
	global_load_lds_dwordx4 v58, s[0:1]
	s_add_i32 m0, s75, 0x1800
	v_mfma_f32_16x16x32_bf16 v[124:127], v[100:103], v[116:119], v[124:127]
	global_load_lds_dwordx4 v59, s[0:1]
	s_add_i32 m0, s75, 0x1c00
	v_mfma_f32_16x16x32_bf16 v[124:127], v[104:107], v[120:123], v[124:127]
	global_load_lds_dwordx4 v60, s[0:1]
	s_add_i32 m0, s75, 0x2000
	s_nop 0
	global_load_lds_dwordx4 v61, s[0:1]
	s_nop 5
	s_mov_b64 exec, 0xffff
	ds_write_b128 v86, v[124:127] offset:3328
	s_mov_b64 exec, -1
	s_waitcnt vmcnt(8)
	ds_read_b128 v[108:111], v74 offset:9216
	ds_read_b128 v[112:115], v75 offset:9216
	ds_read_b128 v[116:119], v76 offset:9216
	ds_read_b128 v[120:123], v77 offset:9216
	s_waitcnt lgkmcnt(0)
	v_mfma_f32_16x16x32_bf16 v[124:127], v[92:95], v[108:111], 0
	s_add_i32 m0, s75, 0x2400
	v_mfma_f32_16x16x32_bf16 v[124:127], v[96:99], v[112:115], v[124:127]
	global_load_lds_dwordx4 v62, s[0:1]
	s_add_i32 m0, s75, 0x2800
	v_mfma_f32_16x16x32_bf16 v[124:127], v[100:103], v[116:119], v[124:127]
	global_load_lds_dwordx4 v63, s[0:1]
	s_add_i32 m0, s75, 0x2c00
	v_mfma_f32_16x16x32_bf16 v[124:127], v[104:107], v[120:123], v[124:127]
	global_load_lds_dwordx4 v64, s[0:1]
	s_add_i32 m0, s75, 0x3000
	s_nop 0
	global_load_lds_dwordx4 v65, s[0:1]
	s_nop 5
	s_mov_b64 exec, 0xffff
	ds_write_b128 v86, v[124:127] offset:3584
	s_mov_b64 exec, -1
	s_waitcnt vmcnt(8)
	ds_read_b128 v[108:111], v74 offset:13312
	ds_read_b128 v[112:115], v75 offset:13312
	ds_read_b128 v[116:119], v76 offset:13312
	ds_read_b128 v[120:123], v77 offset:13312
	s_waitcnt lgkmcnt(0)
	v_mfma_f32_16x16x32_bf16 v[124:127], v[92:95], v[108:111], 0
	s_add_i32 m0, s75, 0x3400
	v_mfma_f32_16x16x32_bf16 v[124:127], v[96:99], v[112:115], v[124:127]
	global_load_lds_dwordx4 v66, s[0:1]
	s_add_i32 m0, s75, 0x3800
	v_mfma_f32_16x16x32_bf16 v[124:127], v[100:103], v[116:119], v[124:127]
	global_load_lds_dwordx4 v67, s[0:1]
	s_add_i32 m0, s75, 0x3c00
	v_mfma_f32_16x16x32_bf16 v[124:127], v[104:107], v[120:123], v[124:127]
	global_load_lds_dwordx4 v68, s[0:1]
	s_add_i32 m0, s75, 0x4000
	s_nop 0
	global_load_lds_dwordx4 v69, s[0:1]
	s_nop 5
	s_mov_b64 exec, 0xffff
	ds_write_b128 v86, v[124:127] offset:3840
	s_mov_b64 exec, -1
	s_waitcnt vmcnt(8)
	ds_read_b128 v[108:111], v74 offset:5120
	ds_read_b128 v[112:115], v75 offset:5120
	ds_read_b128 v[116:119], v76 offset:5120
	ds_read_b128 v[120:123], v77 offset:5120
	s_waitcnt lgkmcnt(0)
	v_mfma_f32_16x16x32_bf16 v[124:127], v[92:95], v[108:111], 0
	s_add_i32 m0, s75, 0x1400
	v_mfma_f32_16x16x32_bf16 v[124:127], v[96:99], v[112:115], v[124:127]
	global_load_lds_dwordx4 v70, s[0:1]
	s_add_i32 m0, s75, 0x1800
	v_mfma_f32_16x16x32_bf16 v[124:127], v[100:103], v[116:119], v[124:127]
	global_load_lds_dwordx4 v71, s[0:1]
	s_add_i32 m0, s75, 0x1c00
	v_mfma_f32_16x16x32_bf16 v[124:127], v[104:107], v[120:123], v[124:127]
	global_load_lds_dwordx4 v72, s[0:1]
	s_add_i32 m0, s75, 0x2000
	s_nop 0
	global_load_lds_dwordx4 v73, s[0:1]
	s_nop 5
	s_mov_b64 exec, 0xffff
	ds_write_b128 v86, v[124:127] offset:4096
	s_mov_b64 exec, -1
	s_waitcnt vmcnt(8)
	ds_read_b128 v[108:111], v74 offset:9216
	ds_read_b128 v[112:115], v75 offset:9216
	ds_read_b128 v[116:119], v76 offset:9216
	ds_read_b128 v[120:123], v77 offset:9216
	s_waitcnt lgkmcnt(0)
	v_mfma_f32_16x16x32_bf16 v[124:127], v[92:95], v[108:111], 0
	v_mfma_f32_16x16x32_bf16 v[124:127], v[96:99], v[112:115], v[124:127]
	v_mfma_f32_16x16x32_bf16 v[124:127], v[100:103], v[116:119], v[124:127]
	v_mfma_f32_16x16x32_bf16 v[124:127], v[104:107], v[120:123], v[124:127]
	s_nop 7
	s_nop 0
	s_mov_b64 exec, 0xffff
	ds_write_b128 v86, v[124:127] offset:4352
	s_mov_b64 exec, -1
	s_waitcnt vmcnt(4)
	ds_read_b128 v[108:111], v74 offset:13312
	ds_read_b128 v[112:115], v75 offset:13312
	ds_read_b128 v[116:119], v76 offset:13312
	ds_read_b128 v[120:123], v77 offset:13312
	s_waitcnt lgkmcnt(0)
	v_mfma_f32_16x16x32_bf16 v[124:127], v[92:95], v[108:111], 0
	v_mfma_f32_16x16x32_bf16 v[124:127], v[96:99], v[112:115], v[124:127]
	v_mfma_f32_16x16x32_bf16 v[124:127], v[100:103], v[116:119], v[124:127]
	v_mfma_f32_16x16x32_bf16 v[124:127], v[104:107], v[120:123], v[124:127]
	s_nop 7
	s_nop 0
	s_mov_b64 exec, 0xffff
	ds_write_b128 v86, v[124:127] offset:4608
	s_mov_b64 exec, -1
	s_waitcnt vmcnt(0)
	ds_read_b128 v[108:111], v74 offset:5120
	ds_read_b128 v[112:115], v75 offset:5120
	ds_read_b128 v[116:119], v76 offset:5120
	ds_read_b128 v[120:123], v77 offset:5120
	s_waitcnt lgkmcnt(0)
	v_mfma_f32_16x16x32_bf16 v[124:127], v[92:95], v[108:111], 0
	v_mfma_f32_16x16x32_bf16 v[124:127], v[96:99], v[112:115], v[124:127]
	v_mfma_f32_16x16x32_bf16 v[124:127], v[100:103], v[116:119], v[124:127]
	v_mfma_f32_16x16x32_bf16 v[124:127], v[104:107], v[120:123], v[124:127]
	s_nop 7
	s_nop 0
	s_mov_b64 exec, 0xffff
	ds_write_b128 v86, v[124:127] offset:4864
	s_mov_b64 exec, -1
	s_add_i32 m0, s75, 0x2400
	s_nop 0
	global_load_lds_dwordx4 v10, s[2:3]
	s_add_i32 m0, s75, 0x2800
	s_nop 0
	global_load_lds_dwordx4 v11, s[2:3]
	s_add_i32 m0, s75, 0x2c00
	s_nop 0
	global_load_lds_dwordx4 v12, s[2:3]
	s_add_i32 m0, s75, 0x3000
	s_nop 0
	global_load_lds_dwordx4 v13, s[2:3]
	s_add_i32 m0, s75, 0x3400
	s_nop 0
	global_load_lds_dwordx4 v14, s[2:3]
	s_add_i32 m0, s75, 0x3800
	s_nop 0
	global_load_lds_dwordx4 v15, s[2:3]
	s_add_i32 m0, s75, 0x3c00
	s_nop 0
	global_load_lds_dwordx4 v16, s[2:3]
	s_add_i32 m0, s75, 0x4000
	s_nop 0
	global_load_lds_dwordx4 v17, s[2:3]
	s_waitcnt lgkmcnt(0)
	ds_read_b128 v[108:111], v87 offset:1024
	ds_read_b128 v[112:115], v87 offset:2048
	ds_read_b128 v[116:119], v87 offset:3072
	ds_read_b128 v[120:123], v87 offset:4096
	s_waitcnt lgkmcnt(0)
	s_add_i32 m0, s75, 0x400
	s_nop 0
	global_load_lds_dwordx4 v18, s[2:3]
	s_add_i32 m0, s75, 0x800
	s_nop 0
	global_load_lds_dwordx4 v19, s[2:3]
	s_add_i32 m0, s75, 0xc00
	s_nop 0
	global_load_lds_dwordx4 v20, s[2:3]
	s_add_i32 m0, s75, 0x1000
	s_nop 0
	global_load_lds_dwordx4 v21, s[2:3]
	s_add_i32 m0, s75, 0x1400
	s_nop 0
	global_load_lds_dwordx4 v22, s[2:3]
	s_add_i32 m0, s75, 0x1800
	s_nop 0
	global_load_lds_dwordx4 v23, s[2:3]
	s_add_i32 m0, s75, 0x1c00
	s_nop 0
	global_load_lds_dwordx4 v24, s[2:3]
	s_add_i32 m0, s75, 0x2000
	s_nop 0
	global_load_lds_dwordx4 v25, s[2:3]
	s_cmp_eq_u32 s73, 0x100
	s_cbranch_scc1 .Lau_nomask1
	v_mov_b32_e32 v9, 0xff61b1e6
	v_cndmask_b32_e64 v108, v9, v108, s[24:25]
	v_cndmask_b32_e64 v109, v9, v109, s[24:25]
	v_cndmask_b32_e64 v110, v9, v110, s[24:25]
	v_cndmask_b32_e64 v111, v9, v111, s[24:25]
	v_cndmask_b32_e64 v112, v9, v112, s[26:27]
	v_cndmask_b32_e64 v113, v9, v113, s[26:27]
	v_cndmask_b32_e64 v114, v9, v114, s[26:27]
	v_cndmask_b32_e64 v115, v9, v115, s[26:27]
	v_cndmask_b32_e64 v116, v9, v116, s[28:29]
	v_cndmask_b32_e64 v117, v9, v117, s[28:29]
	v_cndmask_b32_e64 v118, v9, v118, s[28:29]
	v_cndmask_b32_e64 v119, v9, v119, s[28:29]
	v_cndmask_b32_e64 v120, v9, v120, s[30:31]
	v_cndmask_b32_e64 v121, v9, v121, s[30:31]
	v_cndmask_b32_e64 v122, v9, v122, s[30:31]
	v_cndmask_b32_e64 v123, v9, v123, s[30:31]

.Lau_nomask2:
	s_nop 0
	v_add_f32_e32 v216, 0, v108
	v_add_f32_e32 v217, 0, v109
	v_add_f32_e32 v218, 0, v110
	v_add_f32_e32 v219, 0, v111
	v_add_f32_e32 v216, v112, v216
	v_add_f32_e32 v217, v113, v217
	v_add_f32_e32 v218, v114, v218
	v_add_f32_e32 v219, v115, v219
	v_add_f32_e32 v216, v116, v216
	v_add_f32_e32 v217, v117, v217
	v_add_f32_e32 v218, v118, v218
	v_add_f32_e32 v219, v119, v219
	v_add_f32_e32 v216, v120, v216
	v_add_f32_e32 v217, v121, v217
	v_add_f32_e32 v218, v122, v218
	v_add_f32_e32 v219, v123, v219
	v_add_f32_dpp v216, v216, v216 quad_perm:[1,0,3,2] row_mask:0xf bank_mask:0xf bound_ctrl:1
	v_add_f32_dpp v217, v217, v217 quad_perm:[1,0,3,2] row_mask:0xf bank_mask:0xf bound_ctrl:1
	v_add_f32_dpp v218, v218, v218 quad_perm:[1,0,3,2] row_mask:0xf bank_mask:0xf bound_ctrl:1
	v_add_f32_dpp v219, v219, v219 quad_perm:[1,0,3,2] row_mask:0xf bank_mask:0xf bound_ctrl:1
	v_add_f32_dpp v216, v216, v216 quad_perm:[2,3,0,1] row_mask:0xf bank_mask:0xf bound_ctrl:1
	v_add_f32_dpp v217, v217, v217 quad_perm:[2,3,0,1] row_mask:0xf bank_mask:0xf bound_ctrl:1
	v_add_f32_dpp v218, v218, v218 quad_perm:[2,3,0,1] row_mask:0xf bank_mask:0xf bound_ctrl:1
	v_add_f32_dpp v219, v219, v219 quad_perm:[2,3,0,1] row_mask:0xf bank_mask:0xf bound_ctrl:1
	v_add_f32_dpp v216, v216, v216 row_half_mirror row_mask:0xf bank_mask:0xf bound_ctrl:1
	v_add_f32_dpp v217, v217, v217 row_half_mirror row_mask:0xf bank_mask:0xf bound_ctrl:1
	v_add_f32_dpp v218, v218, v218 row_half_mirror row_mask:0xf bank_mask:0xf bound_ctrl:1
	v_add_f32_dpp v219, v219, v219 row_half_mirror row_mask:0xf bank_mask:0xf bound_ctrl:1
	v_add_f32_dpp v216, v216, v216 row_mirror row_mask:0xf bank_mask:0xf bound_ctrl:1
	v_add_f32_dpp v217, v217, v217 row_mirror row_mask:0xf bank_mask:0xf bound_ctrl:1
	v_add_f32_dpp v218, v218, v218 row_mirror row_mask:0xf bank_mask:0xf bound_ctrl:1
	v_add_f32_dpp v219, v219, v219 row_mirror row_mask:0xf bank_mask:0xf bound_ctrl:1
	v_add_f32_dpp v216, v216, v216 row_bcast:15 row_mask:0xa bank_mask:0xf
	v_add_f32_dpp v217, v217, v217 row_bcast:15 row_mask:0xa bank_mask:0xf
	v_add_f32_dpp v218, v218, v218 row_bcast:15 row_mask:0xa bank_mask:0xf
	v_add_f32_dpp v219, v219, v219 row_bcast:15 row_mask:0xa bank_mask:0xf
	v_add_f32_dpp v216, v216, v216 row_bcast:31 row_mask:0xc bank_mask:0xf
	v_add_f32_dpp v217, v217, v217 row_bcast:31 row_mask:0xc bank_mask:0xf
	v_add_f32_dpp v218, v218, v218 row_bcast:31 row_mask:0xc bank_mask:0xf
	v_add_f32_dpp v219, v219, v219 row_bcast:31 row_mask:0xc bank_mask:0xf
	s_nop 0
	v_readlane_b32 s84, v216, 63
	v_readlane_b32 s85, v217, 63
	v_readlane_b32 s86, v218, 63
	v_readlane_b32 s87, v219, 63
	s_nop 1
	v_mov_b32_e32 v216, s84
	v_mov_b32_e32 v217, s85
	v_mov_b32_e32 v218, s86
	v_mov_b32_e32 v219, s87
	v_div_scale_f32 v220, s[8:9], v216, v216, 1.0
	v_div_scale_f32 v221, s[8:9], v217, v217, 1.0
	v_div_scale_f32 v222, s[8:9], v218, v218, 1.0
	v_div_scale_f32 v223, s[8:9], v219, v219, 1.0
	v_rcp_f32_e32 v128, v220
	v_rcp_f32_e32 v129, v221
	v_rcp_f32_e32 v130, v222
	v_rcp_f32_e32 v131, v223
	s_nop 0
	v_fma_f32 v124, -v220, v128, 1.0
	v_fma_f32 v125, -v221, v129, 1.0
	v_fma_f32 v126, -v222, v130, 1.0
	v_fma_f32 v127, -v223, v131, 1.0
	v_fmac_f32_e32 v128, v124, v128
	v_fmac_f32_e32 v129, v125, v129
	v_fmac_f32_e32 v130, v126, v130
	v_fmac_f32_e32 v131, v127, v131
	v_div_scale_f32 v224, vcc, 1.0, v216, 1.0
	v_mul_f32_e32 v225, v224, v128
	v_fma_f32 v134, -v220, v225, v224
	v_fmac_f32_e32 v225, v134, v128
	v_fma_f32 v220, -v220, v225, v224
	s_nop 0
	v_div_fmas_f32 v220, v220, v128, v225
	v_div_fixup_f32 v220, v220, v216, 1.0
	v_div_scale_f32 v224, vcc, 1.0, v217, 1.0
	v_mul_f32_e32 v225, v224, v129
	v_fma_f32 v134, -v221, v225, v224
	v_fmac_f32_e32 v225, v134, v129
	v_fma_f32 v221, -v221, v225, v224
	s_nop 0
	v_div_fmas_f32 v221, v221, v129, v225
	v_div_fixup_f32 v221, v221, v217, 1.0
	v_div_scale_f32 v224, vcc, 1.0, v218, 1.0
	v_mul_f32_e32 v225, v224, v130
	v_fma_f32 v134, -v222, v225, v224
	v_fmac_f32_e32 v225, v134, v130
	v_fma_f32 v222, -v222, v225, v224
	s_nop 0
	v_div_fmas_f32 v222, v222, v130, v225
	v_div_fixup_f32 v222, v222, v218, 1.0
	v_div_scale_f32 v224, vcc, 1.0, v219, 1.0
	v_mul_f32_e32 v225, v224, v131
	v_fma_f32 v134, -v223, v225, v224
	v_fmac_f32_e32 v225, v134, v131
	v_fma_f32 v223, -v223, v225, v224
	s_nop 0
	v_div_fmas_f32 v223, v223, v131, v225
	v_div_fixup_f32 v223, v223, v219, 1.0
	v_mul_f32_e32 v108, v108, v220
	v_mul_f32_e32 v109, v109, v221
	v_mul_f32_e32 v110, v110, v222
	v_mul_f32_e32 v111, v111, v223
	v_mul_f32_e32 v112, v112, v220
	v_mul_f32_e32 v113, v113, v221
	v_mul_f32_e32 v114, v114, v222
	v_mul_f32_e32 v115, v115, v223
	v_mul_f32_e32 v116, v116, v220
	v_mul_f32_e32 v117, v117, v221
	v_mul_f32_e32 v118, v118, v222
	v_mul_f32_e32 v119, v119, v223
	v_mul_f32_e32 v120, v120, v220
	v_mul_f32_e32 v121, v121, v221
	v_mul_f32_e32 v122, v122, v222
	v_mul_f32_e32 v123, v123, v223
	v_cvt_pk_bf16_f32 v108, v108, v108
	v_cvt_pk_bf16_f32 v109, v109, v109
	v_cvt_pk_bf16_f32 v110, v110, v110
	v_cvt_pk_bf16_f32 v111, v111, v111
	v_cvt_pk_bf16_f32 v112, v112, v112
	v_cvt_pk_bf16_f32 v113, v113, v113
	v_cvt_pk_bf16_f32 v114, v114, v114
	v_cvt_pk_bf16_f32 v115, v115, v115
	v_cvt_pk_bf16_f32 v116, v116, v116
	v_cvt_pk_bf16_f32 v117, v117, v117
	v_cvt_pk_bf16_f32 v118, v118, v118
	v_cvt_pk_bf16_f32 v119, v119, v119
	v_cvt_pk_bf16_f32 v120, v120, v120
	v_cvt_pk_bf16_f32 v121, v121, v121
	v_cvt_pk_bf16_f32 v122, v122, v122
	v_cvt_pk_bf16_f32 v123, v123, v123
	ds_write_b16 v88, v108 offset:0
	ds_write_b16 v88, v109 offset:512
	ds_write_b16 v88, v110 offset:1024
	ds_write_b16 v88, v111 offset:1536
	ds_write_b16 v88, v112 offset:128
	ds_write_b16 v88, v113 offset:640
	ds_write_b16 v88, v114 offset:1152
	ds_write_b16 v88, v115 offset:1664
	ds_write_b16 v88, v116 offset:256
	ds_write_b16 v88, v117 offset:768
	ds_write_b16 v88, v118 offset:1280
	ds_write_b16 v88, v119 offset:1792
	ds_write_b16 v88, v120 offset:384
	ds_write_b16 v88, v121 offset:896
	ds_write_b16 v88, v122 offset:1408
	ds_write_b16 v88, v123 offset:1920
	s_waitcnt vmcnt(8)
	s_waitcnt lgkmcnt(0)
	ds_read_b128 v[172:175], v89 offset:0
	ds_read_b64_tr_b16 v[140:141], v78 offset:9216
	ds_read_b64_tr_b16 v[142:143], v78 offset:10240
	ds_read_b64_tr_b16 v[144:145], v79 offset:9216
	ds_read_b64_tr_b16 v[146:147], v79 offset:10240
	ds_read_b64_tr_b16 v[148:149], v80 offset:9216
	ds_read_b64_tr_b16 v[150:151], v80 offset:10240
	ds_read_b64_tr_b16 v[152:153], v81 offset:9216
	ds_read_b64_tr_b16 v[154:155], v81 offset:10240
	ds_read_b64_tr_b16 v[156:157], v82 offset:9216
	ds_read_b64_tr_b16 v[158:159], v82 offset:10240
	ds_read_b64_tr_b16 v[160:161], v83 offset:9216
	ds_read_b64_tr_b16 v[162:163], v83 offset:10240
	ds_read_b64_tr_b16 v[164:165], v84 offset:9216
	ds_read_b64_tr_b16 v[166:167], v84 offset:10240
	ds_read_b64_tr_b16 v[168:169], v85 offset:9216
	ds_read_b64_tr_b16 v[170:171], v85 offset:10240
	s_waitcnt lgkmcnt(0)
	v_mfma_f32_16x16x32_bf16 v[184:187], v[172:175], v[140:143], 0
	s_add_i32 m0, s75, 0x2400
	v_mfma_f32_16x16x32_bf16 v[188:191], v[172:175], v[144:147], 0
	global_load_lds_dwordx4 v26, s[2:3]
	s_add_i32 m0, s75, 0x2800
	v_mfma_f32_16x16x32_bf16 v[192:195], v[172:175], v[148:151], 0
	global_load_lds_dwordx4 v27, s[2:3]
	s_add_i32 m0, s75, 0x2c00
	v_mfma_f32_16x16x32_bf16 v[196:199], v[172:175], v[152:155], 0
	global_load_lds_dwordx4 v28, s[2:3]
	s_add_i32 m0, s75, 0x3000
	v_mfma_f32_16x16x32_bf16 v[200:203], v[172:175], v[156:159], 0
	global_load_lds_dwordx4 v29, s[2:3]
	s_add_i32 m0, s75, 0x3400
	v_mfma_f32_16x16x32_bf16 v[204:207], v[172:175], v[160:163], 0
	global_load_lds_dwordx4 v30, s[2:3]
	s_add_i32 m0, s75, 0x3800
	v_mfma_f32_16x16x32_bf16 v[208:211], v[172:175], v[164:167], 0
	global_load_lds_dwordx4 v31, s[2:3]
	s_add_i32 m0, s75, 0x3c00
	v_mfma_f32_16x16x32_bf16 v[212:215], v[172:175], v[168:171], 0
	global_load_lds_dwordx4 v32, s[2:3]
	s_add_i32 m0, s75, 0x4000
	s_nop 0
	global_load_lds_dwordx4 v33, s[2:3]
	s_waitcnt vmcnt(8)
	ds_read_b128 v[172:175], v89 offset:64
	ds_read_b64_tr_b16 v[140:141], v78 offset:1024
	ds_read_b64_tr_b16 v[142:143], v78 offset:2048
	ds_read_b64_tr_b16 v[144:145], v79 offset:1024
	ds_read_b64_tr_b16 v[146:147], v79 offset:2048
	ds_read_b64_tr_b16 v[148:149], v80 offset:1024
	ds_read_b64_tr_b16 v[150:151], v80 offset:2048
	ds_read_b64_tr_b16 v[152:153], v81 offset:1024
	ds_read_b64_tr_b16 v[154:155], v81 offset:2048
	ds_read_b64_tr_b16 v[156:157], v82 offset:1024
	ds_read_b64_tr_b16 v[158:159], v82 offset:2048
	ds_read_b64_tr_b16 v[160:161], v83 offset:1024
	ds_read_b64_tr_b16 v[162:163], v83 offset:2048
	ds_read_b64_tr_b16 v[164:165], v84 offset:1024
	ds_read_b64_tr_b16 v[166:167], v84 offset:2048
	ds_read_b64_tr_b16 v[168:169], v85 offset:1024
	ds_read_b64_tr_b16 v[170:171], v85 offset:2048
	s_waitcnt lgkmcnt(0)
	v_mfma_f32_16x16x32_bf16 v[184:187], v[172:175], v[140:143], v[184:187]
	s_add_i32 m0, s75, 0x400
	v_mfma_f32_16x16x32_bf16 v[188:191], v[172:175], v[144:147], v[188:191]
	global_load_lds_dwordx4 v34, s[2:3]
	s_add_i32 m0, s75, 0x800
	v_mfma_f32_16x16x32_bf16 v[192:195], v[172:175], v[148:151], v[192:195]
	global_load_lds_dwordx4 v35, s[2:3]
	s_add_i32 m0, s75, 0xc00
	v_mfma_f32_16x16x32_bf16 v[196:199], v[172:175], v[152:155], v[196:199]
	global_load_lds_dwordx4 v36, s[2:3]
	s_add_i32 m0, s75, 0x1000
	v_mfma_f32_16x16x32_bf16 v[200:203], v[172:175], v[156:159], v[200:203]
	global_load_lds_dwordx4 v37, s[2:3]
	s_add_i32 m0, s75, 0x1400
	v_mfma_f32_16x16x32_bf16 v[204:207], v[172:175], v[160:163], v[204:207]
	global_load_lds_dwordx4 v38, s[2:3]
	s_add_i32 m0, s75, 0x1800
	v_mfma_f32_16x16x32_bf16 v[208:211], v[172:175], v[164:167], v[208:211]
	global_load_lds_dwordx4 v39, s[2:3]
	s_add_i32 m0, s75, 0x1c00
	v_mfma_f32_16x16x32_bf16 v[212:215], v[172:175], v[168:171], v[212:215]
	global_load_lds_dwordx4 v40, s[2:3]
	s_add_i32 m0, s75, 0x2000
	s_nop 0
	global_load_lds_dwordx4 v41, s[2:3]
	s_waitcnt vmcnt(8)
	ds_read_b128 v[172:175], v89 offset:128
	ds_read_b64_tr_b16 v[140:141], v78 offset:9216
	ds_read_b64_tr_b16 v[142:143], v78 offset:10240
	ds_read_b64_tr_b16 v[144:145], v79 offset:9216
	ds_read_b64_tr_b16 v[146:147], v79 offset:10240
	ds_read_b64_tr_b16 v[148:149], v80 offset:9216
	ds_read_b64_tr_b16 v[150:151], v80 offset:10240
	ds_read_b64_tr_b16 v[152:153], v81 offset:9216
	ds_read_b64_tr_b16 v[154:155], v81 offset:10240
	ds_read_b64_tr_b16 v[156:157], v82 offset:9216
	ds_read_b64_tr_b16 v[158:159], v82 offset:10240
	ds_read_b64_tr_b16 v[160:161], v83 offset:9216
	ds_read_b64_tr_b16 v[162:163], v83 offset:10240
	ds_read_b64_tr_b16 v[164:165], v84 offset:9216
	ds_read_b64_tr_b16 v[166:167], v84 offset:10240
	ds_read_b64_tr_b16 v[168:169], v85 offset:9216
	ds_read_b64_tr_b16 v[170:171], v85 offset:10240
	s_waitcnt lgkmcnt(0)
	v_mfma_f32_16x16x32_bf16 v[184:187], v[172:175], v[140:143], v[184:187]
	s_add_i32 m0, s75, 0x2400
	v_mfma_f32_16x16x32_bf16 v[188:191], v[172:175], v[144:147], v[188:191]
	global_load_lds_dwordx4 v42, s[2:3]
	s_add_i32 m0, s75, 0x2800
	v_mfma_f32_16x16x32_bf16 v[192:195], v[172:175], v[148:151], v[192:195]
	global_load_lds_dwordx4 v43, s[2:3]
	s_add_i32 m0, s75, 0x2c00
	v_mfma_f32_16x16x32_bf16 v[196:199], v[172:175], v[152:155], v[196:199]
	global_load_lds_dwordx4 v44, s[2:3]
	s_add_i32 m0, s75, 0x3000
	v_mfma_f32_16x16x32_bf16 v[200:203], v[172:175], v[156:159], v[200:203]
	global_load_lds_dwordx4 v45, s[2:3]
	s_add_i32 m0, s75, 0x3400
	v_mfma_f32_16x16x32_bf16 v[204:207], v[172:175], v[160:163], v[204:207]
	global_load_lds_dwordx4 v46, s[2:3]
	s_add_i32 m0, s75, 0x3800
	v_mfma_f32_16x16x32_bf16 v[208:211], v[172:175], v[164:167], v[208:211]
	global_load_lds_dwordx4 v47, s[2:3]
	s_add_i32 m0, s75, 0x3c00
	v_mfma_f32_16x16x32_bf16 v[212:215], v[172:175], v[168:171], v[212:215]
	global_load_lds_dwordx4 v48, s[2:3]
	s_add_i32 m0, s75, 0x4000
	s_nop 0
	global_load_lds_dwordx4 v49, s[2:3]
	s_waitcnt vmcnt(8)
	ds_read_b128 v[172:175], v89 offset:192
	ds_read_b64_tr_b16 v[140:141], v78 offset:1024
	ds_read_b64_tr_b16 v[142:143], v78 offset:2048
	ds_read_b64_tr_b16 v[144:145], v79 offset:1024
	ds_read_b64_tr_b16 v[146:147], v79 offset:2048
	ds_read_b64_tr_b16 v[148:149], v80 offset:1024
	ds_read_b64_tr_b16 v[150:151], v80 offset:2048
	ds_read_b64_tr_b16 v[152:153], v81 offset:1024
	ds_read_b64_tr_b16 v[154:155], v81 offset:2048
	ds_read_b64_tr_b16 v[156:157], v82 offset:1024
	ds_read_b64_tr_b16 v[158:159], v82 offset:2048
	ds_read_b64_tr_b16 v[160:161], v83 offset:1024
	ds_read_b64_tr_b16 v[162:163], v83 offset:2048
	ds_read_b64_tr_b16 v[164:165], v84 offset:1024
	ds_read_b64_tr_b16 v[166:167], v84 offset:2048
	ds_read_b64_tr_b16 v[168:169], v85 offset:1024
	ds_read_b64_tr_b16 v[170:171], v85 offset:2048
	s_waitcnt lgkmcnt(0)
	v_mfma_f32_16x16x32_bf16 v[184:187], v[172:175], v[140:143], v[184:187]
	s_add_i32 m0, s75, 0x400
	v_mfma_f32_16x16x32_bf16 v[188:191], v[172:175], v[144:147], v[188:191]
	global_load_lds_dwordx4 v50, s[2:3]
	s_add_i32 m0, s75, 0x800
	v_mfma_f32_16x16x32_bf16 v[192:195], v[172:175], v[148:151], v[192:195]
	global_load_lds_dwordx4 v51, s[2:3]
	s_add_i32 m0, s75, 0xc00
	v_mfma_f32_16x16x32_bf16 v[196:199], v[172:175], v[152:155], v[196:199]
	global_load_lds_dwordx4 v52, s[2:3]
	s_add_i32 m0, s75, 0x1000
	v_mfma_f32_16x16x32_bf16 v[200:203], v[172:175], v[156:159], v[200:203]
	global_load_lds_dwordx4 v53, s[2:3]
	s_add_i32 m0, s75, 0x1400
	v_mfma_f32_16x16x32_bf16 v[204:207], v[172:175], v[160:163], v[204:207]
	global_load_lds_dwordx4 v54, s[2:3]
	s_add_i32 m0, s75, 0x1800
	v_mfma_f32_16x16x32_bf16 v[208:211], v[172:175], v[164:167], v[208:211]
	global_load_lds_dwordx4 v55, s[2:3]
	s_add_i32 m0, s75, 0x1c00
	v_mfma_f32_16x16x32_bf16 v[212:215], v[172:175], v[168:171], v[212:215]
	global_load_lds_dwordx4 v56, s[2:3]
	s_add_i32 m0, s75, 0x2000
	s_nop 0
	global_load_lds_dwordx4 v57, s[2:3]
	s_waitcnt vmcnt(8)
	ds_read_b128 v[172:175], v89 offset:256
	ds_read_b64_tr_b16 v[140:141], v78 offset:9216
	ds_read_b64_tr_b16 v[142:143], v78 offset:10240
	ds_read_b64_tr_b16 v[144:145], v79 offset:9216
	ds_read_b64_tr_b16 v[146:147], v79 offset:10240
	ds_read_b64_tr_b16 v[148:149], v80 offset:9216
	ds_read_b64_tr_b16 v[150:151], v80 offset:10240
	ds_read_b64_tr_b16 v[152:153], v81 offset:9216
	ds_read_b64_tr_b16 v[154:155], v81 offset:10240
	ds_read_b64_tr_b16 v[156:157], v82 offset:9216
	ds_read_b64_tr_b16 v[158:159], v82 offset:10240
	ds_read_b64_tr_b16 v[160:161], v83 offset:9216
	ds_read_b64_tr_b16 v[162:163], v83 offset:10240
	ds_read_b64_tr_b16 v[164:165], v84 offset:9216
	ds_read_b64_tr_b16 v[166:167], v84 offset:10240
	ds_read_b64_tr_b16 v[168:169], v85 offset:9216
	ds_read_b64_tr_b16 v[170:171], v85 offset:10240
	s_waitcnt lgkmcnt(0)
	v_mfma_f32_16x16x32_bf16 v[184:187], v[172:175], v[140:143], v[184:187]
	s_add_i32 m0, s75, 0x2400
	v_mfma_f32_16x16x32_bf16 v[188:191], v[172:175], v[144:147], v[188:191]
	global_load_lds_dwordx4 v58, s[2:3]
	s_add_i32 m0, s75, 0x2800
	v_mfma_f32_16x16x32_bf16 v[192:195], v[172:175], v[148:151], v[192:195]
	global_load_lds_dwordx4 v59, s[2:3]
	s_add_i32 m0, s75, 0x2c00
	v_mfma_f32_16x16x32_bf16 v[196:199], v[172:175], v[152:155], v[196:199]
	global_load_lds_dwordx4 v60, s[2:3]
	s_add_i32 m0, s75, 0x3000
	v_mfma_f32_16x16x32_bf16 v[200:203], v[172:175], v[156:159], v[200:203]
	global_load_lds_dwordx4 v61, s[2:3]
	s_add_i32 m0, s75, 0x3400
	v_mfma_f32_16x16x32_bf16 v[204:207], v[172:175], v[160:163], v[204:207]
	global_load_lds_dwordx4 v62, s[2:3]
	s_add_i32 m0, s75, 0x3800
	v_mfma_f32_16x16x32_bf16 v[208:211], v[172:175], v[164:167], v[208:211]
	global_load_lds_dwordx4 v63, s[2:3]
	s_add_i32 m0, s75, 0x3c00
	v_mfma_f32_16x16x32_bf16 v[212:215], v[172:175], v[168:171], v[212:215]
	global_load_lds_dwordx4 v64, s[2:3]
	s_add_i32 m0, s75, 0x4000
	s_nop 0
	global_load_lds_dwordx4 v65, s[2:3]
	s_waitcnt vmcnt(8)
	ds_read_b128 v[172:175], v89 offset:320
	ds_read_b64_tr_b16 v[140:141], v78 offset:1024
	ds_read_b64_tr_b16 v[142:143], v78 offset:2048
	ds_read_b64_tr_b16 v[144:145], v79 offset:1024
	ds_read_b64_tr_b16 v[146:147], v79 offset:2048
	ds_read_b64_tr_b16 v[148:149], v80 offset:1024
	ds_read_b64_tr_b16 v[150:151], v80 offset:2048
	ds_read_b64_tr_b16 v[152:153], v81 offset:1024
	ds_read_b64_tr_b16 v[154:155], v81 offset:2048
	ds_read_b64_tr_b16 v[156:157], v82 offset:1024
	ds_read_b64_tr_b16 v[158:159], v82 offset:2048
	ds_read_b64_tr_b16 v[160:161], v83 offset:1024
	ds_read_b64_tr_b16 v[162:163], v83 offset:2048
	ds_read_b64_tr_b16 v[164:165], v84 offset:1024
	ds_read_b64_tr_b16 v[166:167], v84 offset:2048
	ds_read_b64_tr_b16 v[168:169], v85 offset:1024
	ds_read_b64_tr_b16 v[170:171], v85 offset:2048
	s_waitcnt lgkmcnt(0)
	v_mfma_f32_16x16x32_bf16 v[184:187], v[172:175], v[140:143], v[184:187]
	s_add_i32 m0, s75, 0x400
	v_mfma_f32_16x16x32_bf16 v[188:191], v[172:175], v[144:147], v[188:191]
	global_load_lds_dwordx4 v66, s[2:3]
	s_add_i32 m0, s75, 0x800
	v_mfma_f32_16x16x32_bf16 v[192:195], v[172:175], v[148:151], v[192:195]
	global_load_lds_dwordx4 v67, s[2:3]
	s_add_i32 m0, s75, 0xc00
	v_mfma_f32_16x16x32_bf16 v[196:199], v[172:175], v[152:155], v[196:199]
	global_load_lds_dwordx4 v68, s[2:3]
	s_add_i32 m0, s75, 0x1000
	v_mfma_f32_16x16x32_bf16 v[200:203], v[172:175], v[156:159], v[200:203]
	global_load_lds_dwordx4 v69, s[2:3]
	s_add_i32 m0, s75, 0x1400
	v_mfma_f32_16x16x32_bf16 v[204:207], v[172:175], v[160:163], v[204:207]
	global_load_lds_dwordx4 v70, s[2:3]
	s_add_i32 m0, s75, 0x1800
	v_mfma_f32_16x16x32_bf16 v[208:211], v[172:175], v[164:167], v[208:211]
	global_load_lds_dwordx4 v71, s[2:3]
	s_add_i32 m0, s75, 0x1c00
	v_mfma_f32_16x16x32_bf16 v[212:215], v[172:175], v[168:171], v[212:215]
	global_load_lds_dwordx4 v72, s[2:3]
	s_add_i32 m0, s75, 0x2000
	s_nop 0
	global_load_lds_dwordx4 v73, s[2:3]
	s_waitcnt vmcnt(8)
	ds_read_b128 v[172:175], v89 offset:384
	ds_read_b64_tr_b16 v[140:141], v78 offset:9216
	ds_read_b64_tr_b16 v[142:143], v78 offset:10240
	ds_read_b64_tr_b16 v[144:145], v79 offset:9216
	ds_read_b64_tr_b16 v[146:147], v79 offset:10240
	ds_read_b64_tr_b16 v[148:149], v80 offset:9216
	ds_read_b64_tr_b16 v[150:151], v80 offset:10240
	ds_read_b64_tr_b16 v[152:153], v81 offset:9216
	ds_read_b64_tr_b16 v[154:155], v81 offset:10240
	ds_read_b64_tr_b16 v[156:157], v82 offset:9216
	ds_read_b64_tr_b16 v[158:159], v82 offset:10240
	ds_read_b64_tr_b16 v[160:161], v83 offset:9216
	ds_read_b64_tr_b16 v[162:163], v83 offset:10240
	ds_read_b64_tr_b16 v[164:165], v84 offset:9216
	ds_read_b64_tr_b16 v[166:167], v84 offset:10240
	ds_read_b64_tr_b16 v[168:169], v85 offset:9216
	ds_read_b64_tr_b16 v[170:171], v85 offset:10240
	s_waitcnt lgkmcnt(0)
	v_mfma_f32_16x16x32_bf16 v[184:187], v[172:175], v[140:143], v[184:187]
	v_mfma_f32_16x16x32_bf16 v[188:191], v[172:175], v[144:147], v[188:191]
	v_mfma_f32_16x16x32_bf16 v[192:195], v[172:175], v[148:151], v[192:195]
	v_mfma_f32_16x16x32_bf16 v[196:199], v[172:175], v[152:155], v[196:199]
	v_mfma_f32_16x16x32_bf16 v[200:203], v[172:175], v[156:159], v[200:203]
	v_mfma_f32_16x16x32_bf16 v[204:207], v[172:175], v[160:163], v[204:207]
	v_mfma_f32_16x16x32_bf16 v[208:211], v[172:175], v[164:167], v[208:211]
	v_mfma_f32_16x16x32_bf16 v[212:215], v[172:175], v[168:171], v[212:215]
	s_waitcnt vmcnt(0)
	ds_read_b128 v[172:175], v89 offset:448
	ds_read_b64_tr_b16 v[140:141], v78 offset:1024
	ds_read_b64_tr_b16 v[142:143], v78 offset:2048
	ds_read_b64_tr_b16 v[144:145], v79 offset:1024
	ds_read_b64_tr_b16 v[146:147], v79 offset:2048
	ds_read_b64_tr_b16 v[148:149], v80 offset:1024
	ds_read_b64_tr_b16 v[150:151], v80 offset:2048
	ds_read_b64_tr_b16 v[152:153], v81 offset:1024
	ds_read_b64_tr_b16 v[154:155], v81 offset:2048
	ds_read_b64_tr_b16 v[156:157], v82 offset:1024
	ds_read_b64_tr_b16 v[158:159], v82 offset:2048
	ds_read_b64_tr_b16 v[160:161], v83 offset:1024
	ds_read_b64_tr_b16 v[162:163], v83 offset:2048
	ds_read_b64_tr_b16 v[164:165], v84 offset:1024
	ds_read_b64_tr_b16 v[166:167], v84 offset:2048
	ds_read_b64_tr_b16 v[168:169], v85 offset:1024
	ds_read_b64_tr_b16 v[170:171], v85 offset:2048
	s_waitcnt lgkmcnt(0)
	v_mfma_f32_16x16x32_bf16 v[184:187], v[172:175], v[140:143], v[184:187]
	v_mfma_f32_16x16x32_bf16 v[188:191], v[172:175], v[144:147], v[188:191]
	v_mfma_f32_16x16x32_bf16 v[192:195], v[172:175], v[148:151], v[192:195]
	v_mfma_f32_16x16x32_bf16 v[196:199], v[172:175], v[152:155], v[196:199]
	v_mfma_f32_16x16x32_bf16 v[200:203], v[172:175], v[156:159], v[200:203]
	v_mfma_f32_16x16x32_bf16 v[204:207], v[172:175], v[160:163], v[204:207]
	v_mfma_f32_16x16x32_bf16 v[208:211], v[172:175], v[164:167], v[208:211]
	v_mfma_f32_16x16x32_bf16 v[212:215], v[172:175], v[168:171], v[212:215]
	s_nop 7
	s_mov_b64 exec, 0xffff
	ds_write_b128 v132, v[184:187] offset:0
	ds_write_b128 v132, v[188:191] offset:288
	ds_write_b128 v132, v[192:195] offset:576
	ds_write_b128 v132, v[196:199] offset:864
	ds_write_b128 v132, v[200:203] offset:1152
	ds_write_b128 v132, v[204:207] offset:1440
	ds_write_b128 v132, v[208:211] offset:1728
	ds_write_b128 v132, v[212:215] offset:2016
	s_mov_b64 exec, -1
	s_waitcnt lgkmcnt(0)
	ds_read_b32 v140, v133 offset:0
	ds_read_b32 v141, v133 offset:16
	ds_read_b32 v142, v133 offset:32
	ds_read_b32 v143, v133 offset:48
	ds_read_b32 v144, v133 offset:64
	ds_read_b32 v145, v133 offset:80
	ds_read_b32 v146, v133 offset:96
	ds_read_b32 v147, v133 offset:112
	s_waitcnt lgkmcnt(0)
	v_cvt_pk_bf16_f32 v148, v140, v141
	v_cvt_pk_bf16_f32 v149, v142, v143
	v_cvt_pk_bf16_f32 v150, v144, v145
	v_cvt_pk_bf16_f32 v151, v146, v147
	global_store_dwordx4 v90, v[148:151], s[6:7]
	s_add_i32 s71, s71, 1
	s_cmp_lt_u32 s71, 2
	s_cbranch_scc1 .Lau_g
	s_cmp_eq_u32 s74, 0
	s_cbranch_scc0 .Lau_ret1
	v_and_b32_e32 v141, 64, v182
	v_add_u32_e32 v4, 64, v141
	v_xor_b32_e32 v5, 32, v182
	v_cmp_lt_i32_e32 vcc, v5, v4
	s_nop 1
	v_cndmask_b32_e32 v5, v182, v5, vcc
	v_lshlrev_b32_e32 v132, 2, v5
	v_xor_b32_e32 v5, 16, v182
	v_cmp_lt_i32_e32 vcc, v5, v4
	s_nop 1
	v_cndmask_b32_e32 v5, v182, v5, vcc
	v_lshlrev_b32_e32 v133, 2, v5
	v_xor_b32_e32 v5, 8, v182
	v_cmp_lt_i32_e32 vcc, v5, v4
	s_nop 1
	v_cndmask_b32_e32 v5, v182, v5, vcc
	v_lshlrev_b32_e32 v136, 2, v5
	v_xor_b32_e32 v5, 4, v182
	v_cmp_lt_i32_e32 vcc, v5, v4
	s_nop 1
	v_cndmask_b32_e32 v5, v182, v5, vcc
	v_lshlrev_b32_e32 v137, 2, v5
	v_xor_b32_e32 v5, 2, v182
	v_cmp_lt_i32_e32 vcc, v5, v4
	s_nop 1
	v_cndmask_b32_e32 v5, v182, v5, vcc
	v_lshlrev_b32_e32 v139, 2, v5
	v_xor_b32_e32 v5, 1, v182
	v_cmp_lt_i32_e32 vcc, v5, v4
	s_nop 1
	v_cndmask_b32_e32 v5, v182, v5, vcc
	v_lshlrev_b32_e32 v140, 2, v5
	s_branch .Lau_ret0

.LpA_hdr:
	v_ashrrev_i32_e32 v143, 31, v142
	v_lshlrev_b64 v[164:165], 11, v[142:143]
	v_lshl_add_u64 v[162:163], v[144:145], 0, v[164:165]
	global_load_dwordx4 v[2:5], v[162:163], off
	global_load_dwordx4 v[6:9], v[162:163], off offset:16
	v_lshlrev_b64 v[10:11], 9, v[142:143]
	v_lshl_or_b32 v10, v136, 2, v10
	v_lshl_add_u64 v[18:19], s[82:83], 0, v[10:11]
	v_lshl_add_u64 v[20:21], s[64:65], 0, v[10:11]
	s_mov_b32 s33, 0
	s_mov_b32 s34, 0
	v_mov_b32_e32 v180, 0
	v_mov_b32_e32 v181, v139
	v_mov_b32_e32 v178, 0
	v_mov_b32_e32 v179, v139
	v_mov_b32_e32 v176, 0
	v_mov_b32_e32 v177, v139
	v_mov_b32_e32 v174, 0
	v_mov_b32_e32 v175, v139
	v_mov_b32_e32 v172, 0
	v_mov_b32_e32 v173, v139
	v_mov_b32_e32 v170, 0
	v_mov_b32_e32 v171, v139
	v_mov_b32_e32 v168, 0
	v_mov_b32_e32 v169, v139
	v_mov_b32_e32 v166, 0
	v_mov_b32_e32 v167, v139
	s_waitcnt vmcnt(1)
	v_lshlrev_b32_e32 v10, 16, v2
	v_and_b32_e32 v11, 0xffff0000, v2
	v_lshlrev_b32_e32 v12, 16, v3
	v_and_b32_e32 v13, 0xffff0000, v3
	v_lshlrev_b32_e32 v2, 16, v4
	v_and_b32_e32 v3, 0xffff0000, v4
	v_lshlrev_b32_e32 v4, 16, v5
	v_and_b32_e32 v5, 0xffff0000, v5
	s_waitcnt vmcnt(0)
	v_lshlrev_b32_e32 v14, 16, v6
	v_and_b32_e32 v15, 0xffff0000, v6
	v_lshlrev_b32_e32 v16, 16, v7
	v_and_b32_e32 v17, 0xffff0000, v7
	v_lshlrev_b32_e32 v6, 16, v8
	v_and_b32_e32 v7, 0xffff0000, v8
	v_lshlrev_b32_e32 v8, 16, v9
	v_and_b32_e32 v9, 0xffff0000, v9
	ds_write_b128 v201, v[10:13]
	ds_write_b128 v201, v[2:5] offset:16
	ds_write_b128 v201, v[14:17] offset:32
	ds_write_b128 v201, v[6:9] offset:48
	global_load_dword v211, v[18:19], off
	global_load_dword v212, v[18:19], off offset:256
	global_load_dword v213, v[20:21], off
	global_load_dword v214, v[20:21], off offset:256
	v_and_b32_e32 v3, 64, v182
	ds_read_b32 v232, v137
	ds_read_b32 v233, v183
	ds_read_b32 v234, v184
	ds_read_b32 v235, v185
	ds_read_b32 v236, v186
	ds_read_b32 v237, v187
	ds_read_b32 v238, v188
	ds_read_b32 v239, v189
	ds_read_b32 v240, v190
	ds_read_b32 v241, v191
	ds_read_b32 v242, v192
	ds_read_b32 v243, v193
	ds_read_b32 v244, v194
	ds_read_b32 v245, v195
	ds_read_b32 v246, v196
	ds_read_b32 v247, v197
	v_xor_b32_e32 v2, 1, v182
	v_add_u32_e32 v4, 64, v3
	v_cmp_lt_i32_e64 s[2:3], v2, v4
	v_or_b32_e32 v231, v198, v3
	s_nop 0
	v_cndmask_b32_e64 v2, v182, v2, s[2:3]
	v_lshlrev_b32_e32 v205, 2, v2
	v_xor_b32_e32 v2, 2, v182
	v_cmp_lt_i32_e64 s[2:3], v2, v4
	s_nop 1
	v_cndmask_b32_e64 v2, v182, v2, s[2:3]
	v_lshlrev_b32_e32 v206, 2, v2
	v_xor_b32_e32 v2, 4, v182
	v_cmp_lt_i32_e64 s[2:3], v2, v4
	s_nop 1
	v_cndmask_b32_e64 v2, v182, v2, s[2:3]
	v_lshlrev_b32_e32 v207, 2, v2
	v_xor_b32_e32 v2, 8, v182
	v_cmp_lt_i32_e64 s[2:3], v2, v4
	s_nop 1
	v_cndmask_b32_e64 v2, v182, v2, s[2:3]
	v_lshlrev_b32_e32 v208, 2, v2
	v_xor_b32_e32 v2, 16, v182
	v_cmp_lt_i32_e64 s[2:3], v2, v4
	s_nop 1
	v_cndmask_b32_e64 v2, v182, v2, s[2:3]
	v_lshlrev_b32_e32 v209, 2, v2
	v_xor_b32_e32 v2, 32, v182
	v_cmp_lt_i32_e64 s[2:3], v2, v4
	s_nop 1
	v_cndmask_b32_e64 v2, v182, v2, s[2:3]
	v_lshlrev_b32_e32 v210, 2, v2
	s_waitcnt vmcnt(0)
	s_add_i32 s49, s33, 0
	v_readlane_b32 s40, v211, s49
	s_add_i32 s49, s33, 1
	v_readlane_b32 s41, v211, s49
	s_add_i32 s49, s33, 2
	v_readlane_b32 s42, v211, s49
	s_add_i32 s49, s33, 3
	v_readlane_b32 s43, v211, s49
	s_add_i32 s49, s33, 4
	v_readlane_b32 s44, v211, s49
	s_add_i32 s49, s33, 5
	v_readlane_b32 s45, v211, s49
	s_add_i32 s49, s33, 6
	v_readlane_b32 s46, v211, s49
	s_add_i32 s49, s33, 7
	v_readlane_b32 s47, v211, s49
	v_mad_u32_u24 v152, s40, v202, v138
	global_load_dwordx3 v[48:50], v152, s[78:79]
	v_mad_u32_u24 v153, s41, v202, v138
	global_load_dwordx3 v[92:94], v153, s[78:79]
	v_mad_u32_u24 v154, s42, v202, v138
	global_load_dwordx3 v[54:56], v154, s[78:79]
	v_mad_u32_u24 v155, s43, v202, v138
	global_load_dwordx3 v[80:82], v155, s[78:79]
	v_mad_u32_u24 v152, s44, v202, v138
	global_load_dwordx3 v[60:62], v152, s[78:79]
	v_mad_u32_u24 v153, s45, v202, v138
	global_load_dwordx3 v[84:86], v153, s[78:79]
	v_mad_u32_u24 v154, s46, v202, v138
	global_load_dwordx3 v[76:78], v154, s[78:79]
	v_mad_u32_u24 v155, s47, v202, v138
	global_load_dwordx3 v[88:90], v155, s[78:79]
	s_add_i32 s49, s33, 8
	v_readlane_b32 s40, v211, s49
	s_add_i32 s49, s33, 9
	v_readlane_b32 s41, v211, s49
	s_add_i32 s49, s33, 10
	v_readlane_b32 s42, v211, s49
	s_add_i32 s49, s33, 11
	v_readlane_b32 s43, v211, s49
	s_add_i32 s49, s33, 12
	v_readlane_b32 s44, v211, s49
	s_add_i32 s49, s33, 13
	v_readlane_b32 s45, v211, s49
	s_add_i32 s49, s33, 14
	v_readlane_b32 s46, v211, s49
	s_add_i32 s49, s33, 15
	v_readlane_b32 s47, v211, s49
	v_mad_u32_u24 v152, s40, v202, v138
	global_load_dwordx3 v[34:36], v152, s[78:79]
	v_mad_u32_u24 v153, s41, v202, v138
	global_load_dwordx3 v[44:46], v153, s[78:79]
	v_mad_u32_u24 v154, s42, v202, v138
	global_load_dwordx3 v[66:68], v154, s[78:79]
	v_mad_u32_u24 v155, s43, v202, v138
	global_load_dwordx3 v[40:42], v155, s[78:79]
	v_mad_u32_u24 v152, s44, v202, v138
	global_load_dwordx3 v[98:100], v152, s[78:79]
	v_mad_u32_u24 v153, s45, v202, v138
	global_load_dwordx3 v[72:74], v153, s[78:79]
	v_mad_u32_u24 v154, s46, v202, v138
	global_load_dwordx3 v[130:132], v154, s[78:79]
	v_mad_u32_u24 v155, s47, v202, v138
	global_load_dwordx3 v[104:106], v155, s[78:79]
.LpA_kb:
	s_waitcnt vmcnt(8)
	s_cmp_lt_u32 s34, 8
	s_cselect_b64 s[2:3], -1, 0
	s_waitcnt vmcnt(8)
	s_waitcnt lgkmcnt(0)
	v_mov_b32_e32 v51, v92
	v_mov_b32_e32 v52, v93
	v_mov_b32_e32 v53, v94
	v_cvt_scalef32_pk32_f32_fp6 v[2:33], v[48:53], 1.0
	v_pk_mul_f32 v[108:109], v[232:233], v[2:3]
	v_pk_mul_f32 v[110:111], v[232:233], v[18:19]
	v_pk_fma_f32 v[108:109], v[234:235], v[4:5], v[108:109]
	v_pk_fma_f32 v[110:111], v[234:235], v[20:21], v[110:111]
	v_pk_fma_f32 v[108:109], v[236:237], v[6:7], v[108:109]
	v_pk_fma_f32 v[110:111], v[236:237], v[22:23], v[110:111]
	v_pk_fma_f32 v[108:109], v[238:239], v[8:9], v[108:109]
	v_pk_fma_f32 v[110:111], v[238:239], v[24:25], v[110:111]
	v_pk_fma_f32 v[108:109], v[240:241], v[10:11], v[108:109]
	v_pk_fma_f32 v[110:111], v[240:241], v[26:27], v[110:111]
	v_pk_fma_f32 v[108:109], v[242:243], v[12:13], v[108:109]
	v_pk_fma_f32 v[110:111], v[242:243], v[28:29], v[110:111]
	v_pk_fma_f32 v[108:109], v[244:245], v[14:15], v[108:109]
	v_pk_fma_f32 v[110:111], v[244:245], v[30:31], v[110:111]
	v_pk_fma_f32 v[108:109], v[246:247], v[16:17], v[108:109]
	v_pk_fma_f32 v[110:111], v[246:247], v[32:33], v[110:111]
	s_nop 0
	v_add_f32_e32 v112, v108, v109
	v_add_f32_e32 v113, v110, v111
	v_mov_b32_e32 v57, v80
	v_mov_b32_e32 v58, v81
	v_mov_b32_e32 v59, v82
	v_cvt_scalef32_pk32_f32_fp6 v[2:33], v[54:59], 1.0
	v_pk_mul_f32 v[108:109], v[232:233], v[2:3]
	v_pk_mul_f32 v[110:111], v[232:233], v[18:19]
	v_pk_fma_f32 v[108:109], v[234:235], v[4:5], v[108:109]
	v_pk_fma_f32 v[110:111], v[234:235], v[20:21], v[110:111]
	v_pk_fma_f32 v[108:109], v[236:237], v[6:7], v[108:109]
	v_pk_fma_f32 v[110:111], v[236:237], v[22:23], v[110:111]
	v_pk_fma_f32 v[108:109], v[238:239], v[8:9], v[108:109]
	v_pk_fma_f32 v[110:111], v[238:239], v[24:25], v[110:111]
	v_pk_fma_f32 v[108:109], v[240:241], v[10:11], v[108:109]
	v_pk_fma_f32 v[110:111], v[240:241], v[26:27], v[110:111]
	v_pk_fma_f32 v[108:109], v[242:243], v[12:13], v[108:109]
	v_pk_fma_f32 v[110:111], v[242:243], v[28:29], v[110:111]
	v_pk_fma_f32 v[108:109], v[244:245], v[14:15], v[108:109]
	v_pk_fma_f32 v[110:111], v[244:245], v[30:31], v[110:111]
	v_pk_fma_f32 v[108:109], v[246:247], v[16:17], v[108:109]
	v_pk_fma_f32 v[110:111], v[246:247], v[32:33], v[110:111]
	s_nop 0
	v_add_f32_e32 v114, v108, v109
	v_add_f32_e32 v115, v110, v111
	v_mov_b32_e32 v63, v84
	v_mov_b32_e32 v64, v85
	v_mov_b32_e32 v65, v86
	v_cvt_scalef32_pk32_f32_fp6 v[2:33], v[60:65], 1.0
	v_pk_mul_f32 v[108:109], v[232:233], v[2:3]
	v_pk_mul_f32 v[110:111], v[232:233], v[18:19]
	v_pk_fma_f32 v[108:109], v[234:235], v[4:5], v[108:109]
	v_pk_fma_f32 v[110:111], v[234:235], v[20:21], v[110:111]
	v_pk_fma_f32 v[108:109], v[236:237], v[6:7], v[108:109]
	v_pk_fma_f32 v[110:111], v[236:237], v[22:23], v[110:111]
	v_pk_fma_f32 v[108:109], v[238:239], v[8:9], v[108:109]
	v_pk_fma_f32 v[110:111], v[238:239], v[24:25], v[110:111]
	v_pk_fma_f32 v[108:109], v[240:241], v[10:11], v[108:109]
	v_pk_fma_f32 v[110:111], v[240:241], v[26:27], v[110:111]
	v_pk_fma_f32 v[108:109], v[242:243], v[12:13], v[108:109]
	v_pk_fma_f32 v[110:111], v[242:243], v[28:29], v[110:111]
	v_pk_fma_f32 v[108:109], v[244:245], v[14:15], v[108:109]
	v_pk_fma_f32 v[110:111], v[244:245], v[30:31], v[110:111]
	v_pk_fma_f32 v[108:109], v[246:247], v[16:17], v[108:109]
	v_pk_fma_f32 v[110:111], v[246:247], v[32:33], v[110:111]
	s_nop 0
	v_add_f32_e32 v116, v108, v109
	v_add_f32_e32 v117, v110, v111
	v_mov_b32_e32 v79, v88
	v_mov_b32_e32 v80, v89
	v_mov_b32_e32 v81, v90
	v_cvt_scalef32_pk32_f32_fp6 v[2:33], v[76:81], 1.0
	v_pk_mul_f32 v[108:109], v[232:233], v[2:3]
	v_pk_mul_f32 v[110:111], v[232:233], v[18:19]
	v_pk_fma_f32 v[108:109], v[234:235], v[4:5], v[108:109]
	v_pk_fma_f32 v[110:111], v[234:235], v[20:21], v[110:111]
	v_pk_fma_f32 v[108:109], v[236:237], v[6:7], v[108:109]
	v_pk_fma_f32 v[110:111], v[236:237], v[22:23], v[110:111]
	v_pk_fma_f32 v[108:109], v[238:239], v[8:9], v[108:109]
	v_pk_fma_f32 v[110:111], v[238:239], v[24:25], v[110:111]
	v_pk_fma_f32 v[108:109], v[240:241], v[10:11], v[108:109]
	v_pk_fma_f32 v[110:111], v[240:241], v[26:27], v[110:111]
	v_pk_fma_f32 v[108:109], v[242:243], v[12:13], v[108:109]
	v_pk_fma_f32 v[110:111], v[242:243], v[28:29], v[110:111]
	v_pk_fma_f32 v[108:109], v[244:245], v[14:15], v[108:109]
	v_pk_fma_f32 v[110:111], v[244:245], v[30:31], v[110:111]
	v_pk_fma_f32 v[108:109], v[246:247], v[16:17], v[108:109]
	v_pk_fma_f32 v[110:111], v[246:247], v[32:33], v[110:111]
	s_nop 0
	v_add_f32_e32 v2, v108, v109
	v_add_f32_e32 v18, v110, v111
	s_cmp_eq_u32 s33, 0x70
	s_cbranch_scc1 .Lpf_skip_AU
	s_add_i32 s48, s34, 2
	s_cmp_lt_u32 s48, 8
	s_cselect_b64 s[58:59], -1, 0
	v_cndmask_b32_e64 v215, v212, v211, s[58:59]
	s_add_i32 s49, s33, 16
	v_readlane_b32 s40, v215, s49
	s_add_i32 s49, s33, 17
	v_readlane_b32 s41, v215, s49
	s_add_i32 s49, s33, 18
	v_readlane_b32 s42, v215, s49
	s_add_i32 s49, s33, 19
	v_readlane_b32 s43, v215, s49
	s_add_i32 s49, s33, 20
	v_readlane_b32 s44, v215, s49
	s_add_i32 s49, s33, 21
	v_readlane_b32 s45, v215, s49
	s_add_i32 s49, s33, 22
	v_readlane_b32 s46, v215, s49
	s_add_i32 s49, s33, 23
	v_readlane_b32 s47, v215, s49
	v_mad_u32_u24 v152, s40, v202, v138
	global_load_dwordx3 v[48:50], v152, s[78:79]
	v_mad_u32_u24 v153, s41, v202, v138
	global_load_dwordx3 v[92:94], v153, s[78:79]
	v_mad_u32_u24 v154, s42, v202, v138
	global_load_dwordx3 v[54:56], v154, s[78:79]
	v_mad_u32_u24 v155, s43, v202, v138
	global_load_dwordx3 v[80:82], v155, s[78:79]
	v_mad_u32_u24 v152, s44, v202, v138
	global_load_dwordx3 v[60:62], v152, s[78:79]
	v_mad_u32_u24 v153, s45, v202, v138
	global_load_dwordx3 v[84:86], v153, s[78:79]
	v_mad_u32_u24 v154, s46, v202, v138
	global_load_dwordx3 v[76:78], v154, s[78:79]
	v_mad_u32_u24 v155, s47, v202, v138
	global_load_dwordx3 v[88:90], v155, s[78:79]
.Lpf_skip_AU:
	v_cndmask_b32_e64 v3, v112, v113, s[0:1]
	v_cndmask_b32_e64 v5, v114, v115, s[0:1]
	v_cndmask_b32_e64 v6, v116, v117, s[0:1]
	v_cndmask_b32_e64 v7, v2, v18, s[0:1]
	v_cndmask_b32_e64 v4, v113, v112, s[0:1]
	s_nop 0
	v_mov_b32_dpp v3, v3 quad_perm:[1,0,3,2] row_mask:0xf bank_mask:0xf
	v_mov_b32_dpp v5, v5 quad_perm:[1,0,3,2] row_mask:0xf bank_mask:0xf
	v_mov_b32_dpp v6, v6 quad_perm:[1,0,3,2] row_mask:0xf bank_mask:0xf
	v_mov_b32_dpp v7, v7 quad_perm:[1,0,3,2] row_mask:0xf bank_mask:0xf
	v_add_f32_e32 v3, v4, v3
	v_cndmask_b32_e64 v4, v115, v114, s[0:1]
	v_add_f32_e32 v4, v4, v5
	v_cndmask_b32_e64 v5, v117, v116, s[0:1]
	v_cndmask_b32_e64 v2, v18, v2, s[0:1]
	v_add_f32_e32 v5, v5, v6
	v_add_f32_e32 v2, v2, v7
	v_cndmask_b32_e32 v6, v3, v4, vcc
	v_cndmask_b32_e32 v7, v5, v2, vcc
	v_cndmask_b32_e32 v3, v4, v3, vcc
	v_cndmask_b32_e32 v2, v2, v5, vcc
	v_and_or_b32 v5, s33, 56, v231
	v_mov_b32_dpp v6, v6 quad_perm:[2,3,0,1] row_mask:0xf bank_mask:0xf
	v_mov_b32_dpp v7, v7 quad_perm:[2,3,0,1] row_mask:0xf bank_mask:0xf
	v_add_f32_e32 v3, v3, v6
	v_add_f32_e32 v2, v2, v7
	v_cndmask_b32_e64 v4, v3, v2, s[4:5]
	v_cndmask_b32_e64 v2, v2, v3, s[4:5]
	v_lshlrev_b32_e32 v5, 2, v5
	v_cndmask_b32_e64 v7, v214, v213, s[2:3]
	v_mov_b32_dpp v6, v4 row_shl:4 row_mask:0xf bank_mask:0x5
	v_mov_b32_dpp v6, v4 row_shr:4 row_mask:0xf bank_mask:0xa
	ds_bpermute_b32 v7, v5, v7
	v_add_f32_e32 v2, v2, v6
	s_nop 1
	v_mov_b32_dpp v3, v2 row_ror:8 row_mask:0xf bank_mask:0xf
	v_add_f32_e32 v2, v2, v3
	ds_bpermute_b32 v3, v209, v2
	s_waitcnt lgkmcnt(0)
	v_add_f32_e32 v3, v2, v3
	v_mov_b32_e32 v2, v7
	v_mov_b32_e32 v4, v3
	s_nop 1
	v_permlane32_swap_b32 v3, v4
	v_add_f32_e32 v3, v3, v4
	v_mul_f32_e32 v3, 0x3caaaaab, v3
	v_mul_f32_e32 v4, 0x3f3504f3, v3
	v_cmp_nlt_f32_e64 s[2:3], |v4|, 1.0
	s_and_saveexec_b64 s[14:15], s[2:3]
	s_xor_b64 s[14:15], exec, s[14:15]
	s_cbranch_execz .LpA1_erf_else
	v_fma_f32 v5, |v4|, s7, v203
	v_fma_f32 v5, |v4|, v5, s13
	v_fma_f32 v5, |v4|, v5, s17
	v_fma_f32 v5, |v4|, v5, s19
	v_fma_f32 v5, |v4|, v5, s21
	v_fma_f32 v5, |v4|, v5, s23
	v_fma_f32 v5, |v4|, v5, |v4|
	v_mul_f32_e32 v6, 0xbfb8aa3b, v5
	v_fma_f32 v7, v5, s25, -v6
	v_rndne_f32_e32 v8, v6
	v_fmac_f32_e32 v7, 0xb2a5705f, v5
	v_sub_f32_e32 v6, v6, v8
	v_add_f32_e32 v6, v6, v7
	v_cvt_i32_f32_e32 v7, v8
	v_exp_f32_e32 v6, v6
	v_cmp_nlt_f32_e64 s[2:3], s27, v5
	v_ldexp_f32 v6, v6, v7
	s_nop 0
	v_cndmask_b32_e64 v6, 0, v6, s[2:3]
	v_cmp_ngt_f32_e64 s[2:3], s28, v5
	s_nop 1
	v_cndmask_b32_e64 v5, v204, v6, s[2:3]
	v_sub_f32_e32 v5, 1.0, v5

.LpA1_erf_join:
	s_or_b64 exec, exec, s[2:3]
	s_waitcnt lgkmcnt(0)
	v_mul_f32_e32 v2, 0.5, v2
	v_mul_f32_e32 v2, v2, v3
	v_bfi_b32 v3, s29, v5, v4
	v_add_f32_e32 v3, 1.0, v3
	v_mul_f32_e32 v2, v2, v3
	v_mul_f32_e32 v107, 0x3e124925, v2
	v_cmp_eq_u32_e64 s[54:55], s34, v248
	s_sub_i32 s53, s34, 8
	v_cmp_eq_u32_e64 s[56:57], s53, v248
	s_nop 1
	v_cndmask_b32_e64 v249, v249, v107, s[54:55]
	v_cndmask_b32_e64 v255, v255, v107, s[56:57]
	s_add_i32 s34, s34, 1
	s_add_i32 s33, s33, 8
	s_cmp_eq_u32 s33, 0x78
	s_cbranch_scc1 .Lmw0_A
	s_waitcnt vmcnt(8)
	s_branch .Lmw1_A

.Lmw1_A:
	s_cmp_lt_u32 s34, 8
	s_cselect_b64 s[2:3], -1, 0
	s_waitcnt vmcnt(8)
	s_waitcnt lgkmcnt(0)
	v_mov_b32_e32 v37, v44
	v_mov_b32_e32 v38, v45
	v_mov_b32_e32 v39, v46
	v_cvt_scalef32_pk32_f32_fp6 v[2:33], v[34:39], 1.0
	v_pk_mul_f32 v[108:109], v[232:233], v[2:3]
	v_pk_mul_f32 v[110:111], v[232:233], v[18:19]
	v_pk_fma_f32 v[108:109], v[234:235], v[4:5], v[108:109]
	v_pk_fma_f32 v[110:111], v[234:235], v[20:21], v[110:111]
	v_pk_fma_f32 v[108:109], v[236:237], v[6:7], v[108:109]
	v_pk_fma_f32 v[110:111], v[236:237], v[22:23], v[110:111]
	v_pk_fma_f32 v[108:109], v[238:239], v[8:9], v[108:109]
	v_pk_fma_f32 v[110:111], v[238:239], v[24:25], v[110:111]
	v_pk_fma_f32 v[108:109], v[240:241], v[10:11], v[108:109]
	v_pk_fma_f32 v[110:111], v[240:241], v[26:27], v[110:111]
	v_pk_fma_f32 v[108:109], v[242:243], v[12:13], v[108:109]
	v_pk_fma_f32 v[110:111], v[242:243], v[28:29], v[110:111]
	v_pk_fma_f32 v[108:109], v[244:245], v[14:15], v[108:109]
	v_pk_fma_f32 v[110:111], v[244:245], v[30:31], v[110:111]
	v_pk_fma_f32 v[108:109], v[246:247], v[16:17], v[108:109]
	v_pk_fma_f32 v[110:111], v[246:247], v[32:33], v[110:111]
	s_nop 0
	v_add_f32_e32 v112, v108, v109
	v_add_f32_e32 v113, v110, v111
	v_mov_b32_e32 v69, v40
	v_mov_b32_e32 v70, v41
	v_mov_b32_e32 v71, v42
	v_cvt_scalef32_pk32_f32_fp6 v[2:33], v[66:71], 1.0
	v_pk_mul_f32 v[108:109], v[232:233], v[2:3]
	v_pk_mul_f32 v[110:111], v[232:233], v[18:19]
	v_pk_fma_f32 v[108:109], v[234:235], v[4:5], v[108:109]
	v_pk_fma_f32 v[110:111], v[234:235], v[20:21], v[110:111]
	v_pk_fma_f32 v[108:109], v[236:237], v[6:7], v[108:109]
	v_pk_fma_f32 v[110:111], v[236:237], v[22:23], v[110:111]
	v_pk_fma_f32 v[108:109], v[238:239], v[8:9], v[108:109]
	v_pk_fma_f32 v[110:111], v[238:239], v[24:25], v[110:111]
	v_pk_fma_f32 v[108:109], v[240:241], v[10:11], v[108:109]
	v_pk_fma_f32 v[110:111], v[240:241], v[26:27], v[110:111]
	v_pk_fma_f32 v[108:109], v[242:243], v[12:13], v[108:109]
	v_pk_fma_f32 v[110:111], v[242:243], v[28:29], v[110:111]
	v_pk_fma_f32 v[108:109], v[244:245], v[14:15], v[108:109]
	v_pk_fma_f32 v[110:111], v[244:245], v[30:31], v[110:111]
	v_pk_fma_f32 v[108:109], v[246:247], v[16:17], v[108:109]
	v_pk_fma_f32 v[110:111], v[246:247], v[32:33], v[110:111]
	s_nop 0
	v_add_f32_e32 v114, v108, v109
	v_add_f32_e32 v115, v110, v111
	v_mov_b32_e32 v101, v72
	v_mov_b32_e32 v102, v73
	v_mov_b32_e32 v103, v74
	v_cvt_scalef32_pk32_f32_fp6 v[2:33], v[98:103], 1.0
	v_pk_mul_f32 v[108:109], v[232:233], v[2:3]
	v_pk_mul_f32 v[110:111], v[232:233], v[18:19]
	v_pk_fma_f32 v[108:109], v[234:235], v[4:5], v[108:109]
	v_pk_fma_f32 v[110:111], v[234:235], v[20:21], v[110:111]
	v_pk_fma_f32 v[108:109], v[236:237], v[6:7], v[108:109]
	v_pk_fma_f32 v[110:111], v[236:237], v[22:23], v[110:111]
	v_pk_fma_f32 v[108:109], v[238:239], v[8:9], v[108:109]
	v_pk_fma_f32 v[110:111], v[238:239], v[24:25], v[110:111]
	v_pk_fma_f32 v[108:109], v[240:241], v[10:11], v[108:109]
	v_pk_fma_f32 v[110:111], v[240:241], v[26:27], v[110:111]
	v_pk_fma_f32 v[108:109], v[242:243], v[12:13], v[108:109]
	v_pk_fma_f32 v[110:111], v[242:243], v[28:29], v[110:111]
	v_pk_fma_f32 v[108:109], v[244:245], v[14:15], v[108:109]
	v_pk_fma_f32 v[110:111], v[244:245], v[30:31], v[110:111]
	v_pk_fma_f32 v[108:109], v[246:247], v[16:17], v[108:109]
	v_pk_fma_f32 v[110:111], v[246:247], v[32:33], v[110:111]
	s_nop 0
	v_add_f32_e32 v116, v108, v109
	v_add_f32_e32 v117, v110, v111
	v_mov_b32_e32 v133, v104
	v_mov_b32_e32 v134, v105
	v_mov_b32_e32 v135, v106
	v_cvt_scalef32_pk32_f32_fp6 v[2:33], v[130:135], 1.0
	v_pk_mul_f32 v[108:109], v[232:233], v[2:3]
	v_pk_mul_f32 v[110:111], v[232:233], v[18:19]
	v_pk_fma_f32 v[108:109], v[234:235], v[4:5], v[108:109]
	v_pk_fma_f32 v[110:111], v[234:235], v[20:21], v[110:111]
	v_pk_fma_f32 v[108:109], v[236:237], v[6:7], v[108:109]
	v_pk_fma_f32 v[110:111], v[236:237], v[22:23], v[110:111]
	v_pk_fma_f32 v[108:109], v[238:239], v[8:9], v[108:109]
	v_pk_fma_f32 v[110:111], v[238:239], v[24:25], v[110:111]
	v_pk_fma_f32 v[108:109], v[240:241], v[10:11], v[108:109]
	v_pk_fma_f32 v[110:111], v[240:241], v[26:27], v[110:111]
	v_pk_fma_f32 v[108:109], v[242:243], v[12:13], v[108:109]
	v_pk_fma_f32 v[110:111], v[242:243], v[28:29], v[110:111]
	v_pk_fma_f32 v[108:109], v[244:245], v[14:15], v[108:109]
	v_pk_fma_f32 v[110:111], v[244:245], v[30:31], v[110:111]
	v_pk_fma_f32 v[108:109], v[246:247], v[16:17], v[108:109]
	v_pk_fma_f32 v[110:111], v[246:247], v[32:33], v[110:111]
	s_nop 0
	v_add_f32_e32 v2, v108, v109
	v_add_f32_e32 v18, v110, v111
	s_cmp_eq_u32 s33, 0x78
	s_cbranch_scc1 .Lpf_skip_AV
	s_add_i32 s48, s34, 2
	s_cmp_lt_u32 s48, 8
	s_cselect_b64 s[58:59], -1, 0
	v_cndmask_b32_e64 v215, v212, v211, s[58:59]
	s_add_i32 s49, s33, 16
	v_readlane_b32 s40, v215, s49
	s_add_i32 s49, s33, 17
	v_readlane_b32 s41, v215, s49
	s_add_i32 s49, s33, 18
	v_readlane_b32 s42, v215, s49
	s_add_i32 s49, s33, 19
	v_readlane_b32 s43, v215, s49
	s_add_i32 s49, s33, 20
	v_readlane_b32 s44, v215, s49
	s_add_i32 s49, s33, 21
	v_readlane_b32 s45, v215, s49
	s_add_i32 s49, s33, 22
	v_readlane_b32 s46, v215, s49
	s_add_i32 s49, s33, 23
	v_readlane_b32 s47, v215, s49
	v_mad_u32_u24 v152, s40, v202, v138
	global_load_dwordx3 v[34:36], v152, s[78:79]
	v_mad_u32_u24 v153, s41, v202, v138
	global_load_dwordx3 v[44:46], v153, s[78:79]
	v_mad_u32_u24 v154, s42, v202, v138
	global_load_dwordx3 v[66:68], v154, s[78:79]
	v_mad_u32_u24 v155, s43, v202, v138
	global_load_dwordx3 v[40:42], v155, s[78:79]
	v_mad_u32_u24 v152, s44, v202, v138
	global_load_dwordx3 v[98:100], v152, s[78:79]
	v_mad_u32_u24 v153, s45, v202, v138
	global_load_dwordx3 v[72:74], v153, s[78:79]
	v_mad_u32_u24 v154, s46, v202, v138
	global_load_dwordx3 v[130:132], v154, s[78:79]
	v_mad_u32_u24 v155, s47, v202, v138
	global_load_dwordx3 v[104:106], v155, s[78:79]

.LpB_hdr:
	v_ashrrev_i32_e32 v143, 31, v142
	v_lshlrev_b64 v[164:165], 11, v[142:143]
	v_lshl_add_u64 v[162:163], v[144:145], 0, v[164:165]
	v_lshlrev_b64 v[10:11], 9, v[142:143]
	v_lshl_or_b32 v10, v136, 2, v10
	v_lshl_add_u64 v[18:19], s[82:83], 0, v[10:11]
	v_lshl_add_u64 v[20:21], s[64:65], 0, v[10:11]
	s_mov_b32 s33, 0
	s_mov_b32 s34, 0
	v_mov_b32_e32 v180, 0
	v_mov_b32_e32 v181, v139
	v_mov_b32_e32 v178, 0
	v_mov_b32_e32 v179, v139
	v_mov_b32_e32 v176, 0
	v_mov_b32_e32 v177, v139
	v_mov_b32_e32 v174, 0
	v_mov_b32_e32 v175, v139
	v_mov_b32_e32 v172, 0
	v_mov_b32_e32 v173, v139
	v_mov_b32_e32 v170, 0
	v_mov_b32_e32 v171, v139
	v_mov_b32_e32 v168, 0
	v_mov_b32_e32 v169, v139
	v_mov_b32_e32 v166, 0
	v_mov_b32_e32 v167, v139
	global_load_dword v211, v[18:19], off
	global_load_dword v212, v[18:19], off offset:256
	global_load_dword v213, v[20:21], off sc1
	global_load_dword v214, v[20:21], off offset:256 sc1
	v_and_b32_e32 v3, 64, v182
	v_xor_b32_e32 v2, 1, v182
	v_add_u32_e32 v4, 64, v3
	v_cmp_lt_i32_e64 s[2:3], v2, v4
	v_or_b32_e32 v231, v198, v3
	s_nop 0
	v_cndmask_b32_e64 v2, v182, v2, s[2:3]
	v_lshlrev_b32_e32 v205, 2, v2
	v_xor_b32_e32 v2, 2, v182
	v_cmp_lt_i32_e64 s[2:3], v2, v4
	s_nop 1
	v_cndmask_b32_e64 v2, v182, v2, s[2:3]
	v_lshlrev_b32_e32 v206, 2, v2
	v_xor_b32_e32 v2, 4, v182
	v_cmp_lt_i32_e64 s[2:3], v2, v4
	s_nop 1
	v_cndmask_b32_e64 v2, v182, v2, s[2:3]
	v_lshlrev_b32_e32 v207, 2, v2
	v_xor_b32_e32 v2, 8, v182
	v_cmp_lt_i32_e64 s[2:3], v2, v4
	s_nop 1
	v_cndmask_b32_e64 v2, v182, v2, s[2:3]
	v_lshlrev_b32_e32 v208, 2, v2
	v_xor_b32_e32 v2, 16, v182
	v_cmp_lt_i32_e64 s[2:3], v2, v4
	s_nop 1
	v_cndmask_b32_e64 v2, v182, v2, s[2:3]
	v_lshlrev_b32_e32 v209, 2, v2
	v_xor_b32_e32 v2, 32, v182
	v_cmp_lt_i32_e64 s[2:3], v2, v4
	s_nop 1
	v_cndmask_b32_e64 v2, v182, v2, s[2:3]
	v_lshlrev_b32_e32 v210, 2, v2
	s_waitcnt vmcnt(0)
	s_add_i32 s49, s33, 0
	v_readlane_b32 s40, v211, s49
	s_add_i32 s49, s33, 1
	v_readlane_b32 s41, v211, s49
	s_add_i32 s49, s33, 2
	v_readlane_b32 s42, v211, s49
	s_add_i32 s49, s33, 3
	v_readlane_b32 s43, v211, s49
	s_add_i32 s49, s33, 4
	v_readlane_b32 s44, v211, s49
	s_add_i32 s49, s33, 5
	v_readlane_b32 s45, v211, s49
	s_add_i32 s49, s33, 6
	v_readlane_b32 s46, v211, s49
	s_add_i32 s49, s33, 7
	v_readlane_b32 s47, v211, s49
	v_mad_u32_u24 v152, s40, v202, v138
	global_load_dwordx3 v[34:36], v152, s[80:81]
	v_mad_u32_u24 v153, s41, v202, v138
	global_load_dwordx3 v[44:46], v153, s[80:81]
	v_mad_u32_u24 v154, s42, v202, v138
	global_load_dwordx3 v[66:68], v154, s[80:81]
	v_mad_u32_u24 v155, s43, v202, v138
	global_load_dwordx3 v[40:42], v155, s[80:81]
	v_mad_u32_u24 v152, s44, v202, v138
	global_load_dwordx3 v[98:100], v152, s[80:81]
	v_mad_u32_u24 v153, s45, v202, v138
	global_load_dwordx3 v[72:74], v153, s[80:81]
	v_mad_u32_u24 v154, s46, v202, v138
	global_load_dwordx3 v[130:132], v154, s[80:81]
	v_mad_u32_u24 v155, s47, v202, v138
	global_load_dwordx3 v[104:106], v155, s[80:81]
	s_add_i32 s49, s33, 8
	v_readlane_b32 s40, v211, s49
	s_add_i32 s49, s33, 9
	v_readlane_b32 s41, v211, s49
	s_add_i32 s49, s33, 10
	v_readlane_b32 s42, v211, s49
	s_add_i32 s49, s33, 11
	v_readlane_b32 s43, v211, s49
	s_add_i32 s49, s33, 12
	v_readlane_b32 s44, v211, s49
	s_add_i32 s49, s33, 13
	v_readlane_b32 s45, v211, s49
	s_add_i32 s49, s33, 14
	v_readlane_b32 s46, v211, s49
	s_add_i32 s49, s33, 15
	v_readlane_b32 s47, v211, s49
	v_mad_u32_u24 v152, s40, v202, v138
	global_load_dwordx3 v[216:218], v152, s[80:81]
	v_mad_u32_u24 v153, s41, v202, v138
	global_load_dwordx3 v[220:222], v153, s[80:81]
	v_mad_u32_u24 v154, s42, v202, v138
	global_load_dwordx3 v[224:226], v154, s[80:81]
	v_mad_u32_u24 v155, s43, v202, v138
	global_load_dwordx3 v[228:230], v155, s[80:81]
	v_mad_u32_u24 v152, s44, v202, v138
	global_load_dwordx3 v[232:234], v152, s[80:81]
	v_mad_u32_u24 v153, s45, v202, v138
	global_load_dwordx3 v[236:238], v153, s[80:81]
	v_mad_u32_u24 v154, s46, v202, v138
	global_load_dwordx3 v[240:242], v154, s[80:81]
	v_mad_u32_u24 v155, s47, v202, v138
	global_load_dwordx3 v[244:246], v155, s[80:81]
.LpB_kb:
	s_waitcnt vmcnt(8)
	s_cmp_lt_u32 s34, 8
	s_cselect_b64 s[2:3], -1, 0
	v_and_or_b32 v5, s33, 56, v231
	v_lshlrev_b32_e32 v5, 2, v5
	v_cndmask_b32_e64 v2, v214, v213, s[2:3]
	s_nop 0
	ds_bpermute_b32 v107, v5, v2
	s_waitcnt lgkmcnt(0)
	s_nop 0
	v_readlane_b32 s2, v107, 0
	v_readlane_b32 s14, v107, 1
	v_readlane_b32 s16, v107, 2
	v_readlane_b32 s18, v107, 3
	v_readlane_b32 s20, v107, 4
	v_readlane_b32 s22, v107, 5
	v_readlane_b32 s24, v107, 6
	v_readlane_b32 s26, v107, 7
	v_mov_b32_e32 v37, v44
	v_mov_b32_e32 v38, v45
	v_mov_b32_e32 v39, v46
	v_cvt_scalef32_pk32_f32_fp6 v[2:33], v[34:39], 1.0
	v_pk_fma_f32 v[178:179], v[2:3], s[2:3], v[178:179] op_sel_hi:[1,0,1]
	v_pk_fma_f32 v[176:177], v[4:5], s[2:3], v[176:177] op_sel_hi:[1,0,1]
	v_pk_fma_f32 v[174:175], v[6:7], s[2:3], v[174:175] op_sel_hi:[1,0,1]
	v_pk_fma_f32 v[172:173], v[8:9], s[2:3], v[172:173] op_sel_hi:[1,0,1]
	v_pk_fma_f32 v[170:171], v[10:11], s[2:3], v[170:171] op_sel_hi:[1,0,1]
	v_pk_fma_f32 v[168:169], v[12:13], s[2:3], v[168:169] op_sel_hi:[1,0,1]
	v_pk_fma_f32 v[166:167], v[14:15], s[2:3], v[166:167] op_sel_hi:[1,0,1]
	v_pk_fma_f32 v[180:181], v[16:17], s[2:3], v[180:181] op_sel_hi:[1,0,1]
	v_pk_fma_f32 v[178:179], v[18:19], s[14:15], v[178:179] op_sel_hi:[1,0,1]
	v_pk_fma_f32 v[176:177], v[20:21], s[14:15], v[176:177] op_sel_hi:[1,0,1]
	v_pk_fma_f32 v[174:175], v[22:23], s[14:15], v[174:175] op_sel_hi:[1,0,1]
	v_pk_fma_f32 v[172:173], v[24:25], s[14:15], v[172:173] op_sel_hi:[1,0,1]
	v_pk_fma_f32 v[170:171], v[26:27], s[14:15], v[170:171] op_sel_hi:[1,0,1]
	v_pk_fma_f32 v[168:169], v[28:29], s[14:15], v[168:169] op_sel_hi:[1,0,1]
	v_pk_fma_f32 v[166:167], v[30:31], s[14:15], v[166:167] op_sel_hi:[1,0,1]
	v_pk_fma_f32 v[180:181], v[32:33], s[14:15], v[180:181] op_sel_hi:[1,0,1]
	v_mov_b32_e32 v69, v40
	v_mov_b32_e32 v70, v41
	v_mov_b32_e32 v71, v42
	v_cvt_scalef32_pk32_f32_fp6 v[2:33], v[66:71], 1.0
	v_pk_fma_f32 v[178:179], v[2:3], s[16:17], v[178:179] op_sel_hi:[1,0,1]
	v_pk_fma_f32 v[176:177], v[4:5], s[16:17], v[176:177] op_sel_hi:[1,0,1]
	v_pk_fma_f32 v[174:175], v[6:7], s[16:17], v[174:175] op_sel_hi:[1,0,1]
	v_pk_fma_f32 v[172:173], v[8:9], s[16:17], v[172:173] op_sel_hi:[1,0,1]
	v_pk_fma_f32 v[170:171], v[10:11], s[16:17], v[170:171] op_sel_hi:[1,0,1]
	v_pk_fma_f32 v[168:169], v[12:13], s[16:17], v[168:169] op_sel_hi:[1,0,1]
	v_pk_fma_f32 v[166:167], v[14:15], s[16:17], v[166:167] op_sel_hi:[1,0,1]
	v_pk_fma_f32 v[180:181], v[16:17], s[16:17], v[180:181] op_sel_hi:[1,0,1]
	v_pk_fma_f32 v[178:179], v[18:19], s[18:19], v[178:179] op_sel_hi:[1,0,1]
	v_pk_fma_f32 v[176:177], v[20:21], s[18:19], v[176:177] op_sel_hi:[1,0,1]
	v_pk_fma_f32 v[174:175], v[22:23], s[18:19], v[174:175] op_sel_hi:[1,0,1]
	v_pk_fma_f32 v[172:173], v[24:25], s[18:19], v[172:173] op_sel_hi:[1,0,1]
	v_pk_fma_f32 v[170:171], v[26:27], s[18:19], v[170:171] op_sel_hi:[1,0,1]
	v_pk_fma_f32 v[168:169], v[28:29], s[18:19], v[168:169] op_sel_hi:[1,0,1]
	v_pk_fma_f32 v[166:167], v[30:31], s[18:19], v[166:167] op_sel_hi:[1,0,1]
	v_pk_fma_f32 v[180:181], v[32:33], s[18:19], v[180:181] op_sel_hi:[1,0,1]
	v_mov_b32_e32 v101, v72
	v_mov_b32_e32 v102, v73
	v_mov_b32_e32 v103, v74
	v_cvt_scalef32_pk32_f32_fp6 v[2:33], v[98:103], 1.0
	v_pk_fma_f32 v[178:179], v[2:3], s[20:21], v[178:179] op_sel_hi:[1,0,1]
	v_pk_fma_f32 v[176:177], v[4:5], s[20:21], v[176:177] op_sel_hi:[1,0,1]
	v_pk_fma_f32 v[174:175], v[6:7], s[20:21], v[174:175] op_sel_hi:[1,0,1]
	v_pk_fma_f32 v[172:173], v[8:9], s[20:21], v[172:173] op_sel_hi:[1,0,1]
	v_pk_fma_f32 v[170:171], v[10:11], s[20:21], v[170:171] op_sel_hi:[1,0,1]
	v_pk_fma_f32 v[168:169], v[12:13], s[20:21], v[168:169] op_sel_hi:[1,0,1]
	v_pk_fma_f32 v[166:167], v[14:15], s[20:21], v[166:167] op_sel_hi:[1,0,1]
	v_pk_fma_f32 v[180:181], v[16:17], s[20:21], v[180:181] op_sel_hi:[1,0,1]
	v_pk_fma_f32 v[178:179], v[18:19], s[22:23], v[178:179] op_sel_hi:[1,0,1]
	v_pk_fma_f32 v[176:177], v[20:21], s[22:23], v[176:177] op_sel_hi:[1,0,1]
	v_pk_fma_f32 v[174:175], v[22:23], s[22:23], v[174:175] op_sel_hi:[1,0,1]
	v_pk_fma_f32 v[172:173], v[24:25], s[22:23], v[172:173] op_sel_hi:[1,0,1]
	v_pk_fma_f32 v[170:171], v[26:27], s[22:23], v[170:171] op_sel_hi:[1,0,1]
	v_pk_fma_f32 v[168:169], v[28:29], s[22:23], v[168:169] op_sel_hi:[1,0,1]
	v_pk_fma_f32 v[166:167], v[30:31], s[22:23], v[166:167] op_sel_hi:[1,0,1]
	v_pk_fma_f32 v[180:181], v[32:33], s[22:23], v[180:181] op_sel_hi:[1,0,1]
	v_mov_b32_e32 v133, v104
	v_mov_b32_e32 v134, v105
	v_mov_b32_e32 v135, v106
	v_cvt_scalef32_pk32_f32_fp6 v[2:33], v[130:135], 1.0
	s_cmp_eq_u32 s33, 0x70
	s_cbranch_scc1 .Lpf_skip_BV
	s_add_i32 s48, s34, 2
	s_cmp_lt_u32 s48, 8
	s_cselect_b64 s[58:59], -1, 0
	v_cndmask_b32_e64 v215, v212, v211, s[58:59]
	s_add_i32 s49, s33, 16
	v_readlane_b32 s40, v215, s49
	s_add_i32 s49, s33, 17
	v_readlane_b32 s41, v215, s49
	s_add_i32 s49, s33, 18
	v_readlane_b32 s42, v215, s49
	s_add_i32 s49, s33, 19
	v_readlane_b32 s43, v215, s49
	s_add_i32 s49, s33, 20
	v_readlane_b32 s44, v215, s49
	s_add_i32 s49, s33, 21
	v_readlane_b32 s45, v215, s49
	s_add_i32 s49, s33, 22
	v_readlane_b32 s46, v215, s49
	s_add_i32 s49, s33, 23
	v_readlane_b32 s47, v215, s49
	v_mad_u32_u24 v152, s40, v202, v138
	global_load_dwordx3 v[34:36], v152, s[80:81]
	v_mad_u32_u24 v153, s41, v202, v138
	global_load_dwordx3 v[44:46], v153, s[80:81]
	v_mad_u32_u24 v154, s42, v202, v138
	global_load_dwordx3 v[66:68], v154, s[80:81]
	v_mad_u32_u24 v155, s43, v202, v138
	global_load_dwordx3 v[40:42], v155, s[80:81]
	v_mad_u32_u24 v152, s44, v202, v138
	global_load_dwordx3 v[98:100], v152, s[80:81]
	v_mad_u32_u24 v153, s45, v202, v138
	global_load_dwordx3 v[72:74], v153, s[80:81]
	v_mad_u32_u24 v154, s46, v202, v138
	global_load_dwordx3 v[130:132], v154, s[80:81]
	v_mad_u32_u24 v155, s47, v202, v138
	global_load_dwordx3 v[104:106], v155, s[80:81]
.Lpf_skip_BV:
	v_pk_fma_f32 v[178:179], v[2:3], s[24:25], v[178:179] op_sel_hi:[1,0,1]
	v_pk_fma_f32 v[176:177], v[4:5], s[24:25], v[176:177] op_sel_hi:[1,0,1]
	v_pk_fma_f32 v[174:175], v[6:7], s[24:25], v[174:175] op_sel_hi:[1,0,1]
	v_pk_fma_f32 v[172:173], v[8:9], s[24:25], v[172:173] op_sel_hi:[1,0,1]
	v_pk_fma_f32 v[170:171], v[10:11], s[24:25], v[170:171] op_sel_hi:[1,0,1]
	v_pk_fma_f32 v[168:169], v[12:13], s[24:25], v[168:169] op_sel_hi:[1,0,1]
	v_pk_fma_f32 v[166:167], v[14:15], s[24:25], v[166:167] op_sel_hi:[1,0,1]
	v_pk_fma_f32 v[180:181], v[16:17], s[24:25], v[180:181] op_sel_hi:[1,0,1]
	v_pk_fma_f32 v[178:179], v[18:19], s[26:27], v[178:179] op_sel_hi:[1,0,1]
	v_pk_fma_f32 v[176:177], v[20:21], s[26:27], v[176:177] op_sel_hi:[1,0,1]
	v_pk_fma_f32 v[174:175], v[22:23], s[26:27], v[174:175] op_sel_hi:[1,0,1]
	v_pk_fma_f32 v[172:173], v[24:25], s[26:27], v[172:173] op_sel_hi:[1,0,1]
	v_pk_fma_f32 v[170:171], v[26:27], s[26:27], v[170:171] op_sel_hi:[1,0,1]
	v_pk_fma_f32 v[168:169], v[28:29], s[26:27], v[168:169] op_sel_hi:[1,0,1]
	v_pk_fma_f32 v[166:167], v[30:31], s[26:27], v[166:167] op_sel_hi:[1,0,1]
	v_pk_fma_f32 v[180:181], v[32:33], s[26:27], v[180:181] op_sel_hi:[1,0,1]
	s_add_i32 s34, s34, 1
	s_add_i32 s33, s33, 8
	s_cmp_eq_u32 s33, 0x78
	s_cbranch_scc1 .Lmw0_B
	s_waitcnt vmcnt(8)
	s_branch .Lmw1_B

.Lmw1_B:
	s_cmp_lt_u32 s34, 8
	s_cselect_b64 s[2:3], -1, 0
	v_and_or_b32 v5, s33, 56, v231
	v_lshlrev_b32_e32 v5, 2, v5
	v_cndmask_b32_e64 v2, v214, v213, s[2:3]
	s_nop 0
	ds_bpermute_b32 v107, v5, v2
	s_waitcnt lgkmcnt(0)
	s_nop 0
	v_readlane_b32 s2, v107, 0
	v_readlane_b32 s14, v107, 1
	v_readlane_b32 s16, v107, 2
	v_readlane_b32 s18, v107, 3
	v_readlane_b32 s20, v107, 4
	v_readlane_b32 s22, v107, 5
	v_readlane_b32 s24, v107, 6
	v_readlane_b32 s26, v107, 7
	v_mov_b32_e32 v219, v220
	v_mov_b32_e32 v220, v221
	v_mov_b32_e32 v221, v222
	v_cvt_scalef32_pk32_f32_fp6 v[2:33], v[216:221], 1.0
	v_pk_fma_f32 v[178:179], v[2:3], s[2:3], v[178:179] op_sel_hi:[1,0,1]
	v_pk_fma_f32 v[176:177], v[4:5], s[2:3], v[176:177] op_sel_hi:[1,0,1]
	v_pk_fma_f32 v[174:175], v[6:7], s[2:3], v[174:175] op_sel_hi:[1,0,1]
	v_pk_fma_f32 v[172:173], v[8:9], s[2:3], v[172:173] op_sel_hi:[1,0,1]
	v_pk_fma_f32 v[170:171], v[10:11], s[2:3], v[170:171] op_sel_hi:[1,0,1]
	v_pk_fma_f32 v[168:169], v[12:13], s[2:3], v[168:169] op_sel_hi:[1,0,1]
	v_pk_fma_f32 v[166:167], v[14:15], s[2:3], v[166:167] op_sel_hi:[1,0,1]
	v_pk_fma_f32 v[180:181], v[16:17], s[2:3], v[180:181] op_sel_hi:[1,0,1]
	v_pk_fma_f32 v[178:179], v[18:19], s[14:15], v[178:179] op_sel_hi:[1,0,1]
	v_pk_fma_f32 v[176:177], v[20:21], s[14:15], v[176:177] op_sel_hi:[1,0,1]
	v_pk_fma_f32 v[174:175], v[22:23], s[14:15], v[174:175] op_sel_hi:[1,0,1]
	v_pk_fma_f32 v[172:173], v[24:25], s[14:15], v[172:173] op_sel_hi:[1,0,1]
	v_pk_fma_f32 v[170:171], v[26:27], s[14:15], v[170:171] op_sel_hi:[1,0,1]
	v_pk_fma_f32 v[168:169], v[28:29], s[14:15], v[168:169] op_sel_hi:[1,0,1]
	v_pk_fma_f32 v[166:167], v[30:31], s[14:15], v[166:167] op_sel_hi:[1,0,1]
	v_pk_fma_f32 v[180:181], v[32:33], s[14:15], v[180:181] op_sel_hi:[1,0,1]
	v_mov_b32_e32 v227, v228
	v_mov_b32_e32 v228, v229
	v_mov_b32_e32 v229, v230
	v_cvt_scalef32_pk32_f32_fp6 v[2:33], v[224:229], 1.0
	v_pk_fma_f32 v[178:179], v[2:3], s[16:17], v[178:179] op_sel_hi:[1,0,1]
	v_pk_fma_f32 v[176:177], v[4:5], s[16:17], v[176:177] op_sel_hi:[1,0,1]
	v_pk_fma_f32 v[174:175], v[6:7], s[16:17], v[174:175] op_sel_hi:[1,0,1]
	v_pk_fma_f32 v[172:173], v[8:9], s[16:17], v[172:173] op_sel_hi:[1,0,1]
	v_pk_fma_f32 v[170:171], v[10:11], s[16:17], v[170:171] op_sel_hi:[1,0,1]
	v_pk_fma_f32 v[168:169], v[12:13], s[16:17], v[168:169] op_sel_hi:[1,0,1]
	v_pk_fma_f32 v[166:167], v[14:15], s[16:17], v[166:167] op_sel_hi:[1,0,1]
	v_pk_fma_f32 v[180:181], v[16:17], s[16:17], v[180:181] op_sel_hi:[1,0,1]
	v_pk_fma_f32 v[178:179], v[18:19], s[18:19], v[178:179] op_sel_hi:[1,0,1]
	v_pk_fma_f32 v[176:177], v[20:21], s[18:19], v[176:177] op_sel_hi:[1,0,1]
	v_pk_fma_f32 v[174:175], v[22:23], s[18:19], v[174:175] op_sel_hi:[1,0,1]
	v_pk_fma_f32 v[172:173], v[24:25], s[18:19], v[172:173] op_sel_hi:[1,0,1]
	v_pk_fma_f32 v[170:171], v[26:27], s[18:19], v[170:171] op_sel_hi:[1,0,1]
	v_pk_fma_f32 v[168:169], v[28:29], s[18:19], v[168:169] op_sel_hi:[1,0,1]
	v_pk_fma_f32 v[166:167], v[30:31], s[18:19], v[166:167] op_sel_hi:[1,0,1]
	v_pk_fma_f32 v[180:181], v[32:33], s[18:19], v[180:181] op_sel_hi:[1,0,1]
	v_mov_b32_e32 v235, v236
	v_mov_b32_e32 v236, v237
	v_mov_b32_e32 v237, v238
	v_cvt_scalef32_pk32_f32_fp6 v[2:33], v[232:237], 1.0
	v_pk_fma_f32 v[178:179], v[2:3], s[20:21], v[178:179] op_sel_hi:[1,0,1]
	v_pk_fma_f32 v[176:177], v[4:5], s[20:21], v[176:177] op_sel_hi:[1,0,1]
	v_pk_fma_f32 v[174:175], v[6:7], s[20:21], v[174:175] op_sel_hi:[1,0,1]
	v_pk_fma_f32 v[172:173], v[8:9], s[20:21], v[172:173] op_sel_hi:[1,0,1]
	v_pk_fma_f32 v[170:171], v[10:11], s[20:21], v[170:171] op_sel_hi:[1,0,1]
	v_pk_fma_f32 v[168:169], v[12:13], s[20:21], v[168:169] op_sel_hi:[1,0,1]
	v_pk_fma_f32 v[166:167], v[14:15], s[20:21], v[166:167] op_sel_hi:[1,0,1]
	v_pk_fma_f32 v[180:181], v[16:17], s[20:21], v[180:181] op_sel_hi:[1,0,1]
	v_pk_fma_f32 v[178:179], v[18:19], s[22:23], v[178:179] op_sel_hi:[1,0,1]
	v_pk_fma_f32 v[176:177], v[20:21], s[22:23], v[176:177] op_sel_hi:[1,0,1]
	v_pk_fma_f32 v[174:175], v[22:23], s[22:23], v[174:175] op_sel_hi:[1,0,1]
	v_pk_fma_f32 v[172:173], v[24:25], s[22:23], v[172:173] op_sel_hi:[1,0,1]
	v_pk_fma_f32 v[170:171], v[26:27], s[22:23], v[170:171] op_sel_hi:[1,0,1]
	v_pk_fma_f32 v[168:169], v[28:29], s[22:23], v[168:169] op_sel_hi:[1,0,1]
	v_pk_fma_f32 v[166:167], v[30:31], s[22:23], v[166:167] op_sel_hi:[1,0,1]
	v_pk_fma_f32 v[180:181], v[32:33], s[22:23], v[180:181] op_sel_hi:[1,0,1]
	v_mov_b32_e32 v243, v244
	v_mov_b32_e32 v244, v245
	v_mov_b32_e32 v245, v246
	v_cvt_scalef32_pk32_f32_fp6 v[2:33], v[240:245], 1.0
	s_cmp_eq_u32 s33, 0x78
	s_cbranch_scc1 .Lpf_skip_BP
	s_add_i32 s48, s34, 2
	s_cmp_lt_u32 s48, 8
	s_cselect_b64 s[58:59], -1, 0
	v_cndmask_b32_e64 v215, v212, v211, s[58:59]
	s_add_i32 s49, s33, 16
	v_readlane_b32 s40, v215, s49
	s_add_i32 s49, s33, 17
	v_readlane_b32 s41, v215, s49
	s_add_i32 s49, s33, 18
	v_readlane_b32 s42, v215, s49
	s_add_i32 s49, s33, 19
	v_readlane_b32 s43, v215, s49
	s_add_i32 s49, s33, 20
	v_readlane_b32 s44, v215, s49
	s_add_i32 s49, s33, 21
	v_readlane_b32 s45, v215, s49
	s_add_i32 s49, s33, 22
	v_readlane_b32 s46, v215, s49
	s_add_i32 s49, s33, 23
	v_readlane_b32 s47, v215, s49
	v_mad_u32_u24 v152, s40, v202, v138
	global_load_dwordx3 v[216:218], v152, s[80:81]
	v_mad_u32_u24 v153, s41, v202, v138
	global_load_dwordx3 v[220:222], v153, s[80:81]
	v_mad_u32_u24 v154, s42, v202, v138
	global_load_dwordx3 v[224:226], v154, s[80:81]
	v_mad_u32_u24 v155, s43, v202, v138
	global_load_dwordx3 v[228:230], v155, s[80:81]
	v_mad_u32_u24 v152, s44, v202, v138
	global_load_dwordx3 v[232:234], v152, s[80:81]
	v_mad_u32_u24 v153, s45, v202, v138
	global_load_dwordx3 v[236:238], v153, s[80:81]
	v_mad_u32_u24 v154, s46, v202, v138
	global_load_dwordx3 v[240:242], v154, s[80:81]
	v_mad_u32_u24 v155, s47, v202, v138
	global_load_dwordx3 v[244:246], v155, s[80:81]
.Lpf_skip_BP:
	v_pk_fma_f32 v[178:179], v[2:3], s[24:25], v[178:179] op_sel_hi:[1,0,1]
	v_pk_fma_f32 v[176:177], v[4:5], s[24:25], v[176:177] op_sel_hi:[1,0,1]
	v_pk_fma_f32 v[174:175], v[6:7], s[24:25], v[174:175] op_sel_hi:[1,0,1]
	v_pk_fma_f32 v[172:173], v[8:9], s[24:25], v[172:173] op_sel_hi:[1,0,1]
	v_pk_fma_f32 v[170:171], v[10:11], s[24:25], v[170:171] op_sel_hi:[1,0,1]
	v_pk_fma_f32 v[168:169], v[12:13], s[24:25], v[168:169] op_sel_hi:[1,0,1]
	v_pk_fma_f32 v[166:167], v[14:15], s[24:25], v[166:167] op_sel_hi:[1,0,1]
	v_pk_fma_f32 v[180:181], v[16:17], s[24:25], v[180:181] op_sel_hi:[1,0,1]
	v_pk_fma_f32 v[178:179], v[18:19], s[26:27], v[178:179] op_sel_hi:[1,0,1]
	v_pk_fma_f32 v[176:177], v[20:21], s[26:27], v[176:177] op_sel_hi:[1,0,1]
	v_pk_fma_f32 v[174:175], v[22:23], s[26:27], v[174:175] op_sel_hi:[1,0,1]
	v_pk_fma_f32 v[172:173], v[24:25], s[26:27], v[172:173] op_sel_hi:[1,0,1]
	v_pk_fma_f32 v[170:171], v[26:27], s[26:27], v[170:171] op_sel_hi:[1,0,1]
	v_pk_fma_f32 v[168:169], v[28:29], s[26:27], v[168:169] op_sel_hi:[1,0,1]
	v_pk_fma_f32 v[166:167], v[30:31], s[26:27], v[166:167] op_sel_hi:[1,0,1]
	v_pk_fma_f32 v[180:181], v[32:33], s[26:27], v[180:181] op_sel_hi:[1,0,1]
	s_add_i32 s34, s34, 1
	s_add_i32 s33, s33, 8
	s_cmpk_lg_i32 s33, 0x80
	s_cbranch_scc1 .LpB_kb
	s_branch .LpB_epi
